# in-projection GEMM epilogue specialised per activation mode: one dispatch per tile, straight-line vector code, per-group scalar flag logic and branches removed
# baseline (speedup 1.0000x reference)
; __device__ __forceinline__ unsigned cvt_pk_bf16(float lo, float hi) { const f32x2e_t v = {lo, hi}; return __builtin_bit_cast(unsigned, __builtin_convertvector(v, bf16x2e_t)); }
; __device__ __forceinline__ float fsigmoid(float v) { return __builtin_amdgcn_rcpf(1.f + __expf(-v)); }
;     __device__ __forceinline__ void operator()(const f32x4 (&acc)[2][2][4][2], const Unit& u, int wr, int wc, int fr, int fq) const {
;         const int row0 = u.pm * BM + wr * 64 + fr;
;         int mode = 0; const int pn = u.pn;
;         if (kind == 0) {
;             if (pn >= 24) mode = 3;
;             else if ((pn >= 8 && pn < 12) || pn == 18 || pn == 19 || pn == 22 || pn == 23) mode = 2;
;             else if (pn == 12 || pn == 13) mode = 1;
;         }
;         const int col0 = pn * BM + wc * 32 + 8 * fq;
; #pragma unroll
;         for (int ai = 0; ai < 2; ++ai)
; #pragma unroll
;             for (int m = 0; m < 4; ++m) { bf16_t* rowp = Z + (size_t)(row0 + ai * HALF + m * 16) * ldz + col0;
; #pragma unroll
;                 for (int bj = 0; bj < 2; ++bj) { f32x4 v0 = acc[ai][bj][m][0], v1 = acc[ai][bj][m][1];
;                     if (mode == 1) { v0 = v0 * 0.18033688011112042f; v1 = v1 * 0.18033688011112042f; }
;                     else if (mode == 2) {
; #pragma unroll
;                         for (int j = 0; j < 4; ++j) { v0[j] = v0[j] * fsigmoid(v0[j]); v1[j] = v1[j] * fsigmoid(v1[j]); } }
;                     else if (mode == 3) {
; #pragma unroll
;                         for (int j = 0; j < 4; ++j) { v0[j] = fsigmoid(v0[j]); v1[j] = fsigmoid(v1[j]); } }
;                     u32x4 w; w.x = cvt_pk_bf16(v0[0], v0[1]); w.y = cvt_pk_bf16(v0[2], v0[3]); w.z = cvt_pk_bf16(v1[0], v1[1]); w.w = cvt_pk_bf16(v1[2], v1[3]);
;                     *(u32x4*)(rowp + bj * HALF) = w; } }
.LBB0_126:
	s_cmp_lt_u32 s26, 8
	s_cbranch_scc1 .Lepi_class_0
	s_cmp_lt_u32 s26, 12
	s_cbranch_scc1 .Lepi_class_1
	s_cmp_lt_u32 s26, 14
	s_cbranch_scc1 .Lepi_class_2
	s_cmp_lt_u32 s26, 18
	s_cbranch_scc1 .Lepi_class_0
	s_cmp_lt_u32 s26, 20
	s_cbranch_scc1 .Lepi_class_1
	s_cmp_lt_u32 s26, 22
	s_cbranch_scc1 .Lepi_class_0
	s_cmp_lt_u32 s26, 24
	s_cbranch_scc1 .Lepi_class_1
	s_branch .Lepi_class_3
.Lepi_class_0:
	s_mov_b32 s82, 0xca30000
	s_mov_b32 s83, 0x10a40000
	v_mov_b32_e32 v163, v125
	v_mov_b32_e32 v162, v124
	v_mov_b32_e32 v159, v123
	v_mov_b32_e32 v158, v122
	v_mov_b32_e32 v161, v147
	v_mov_b32_e32 v160, v146
	v_mov_b32_e32 v157, v145
	v_mov_b32_e32 v156, v144
	v_lshl_add_u32 v168, s27, 8, v164
	v_lshl_or_b32 v122, s26, 8, v166
	v_mov_b64_e32 v[124:125], s[92:93]
	v_ashrrev_i32_e32 v123, 31, v122
	v_mad_i64_i32 v[124:125], s[8:9], v168, s80, v[124:125]
	v_lshl_add_u64 v[124:125], v[122:123], 1, v[124:125]
	v_cvt_pk_bf16_f32 v144, v156, v157
	v_cvt_pk_bf16_f32 v145, v160, v161
	v_cvt_pk_bf16_f32 v146, v158, v159
	v_cvt_pk_bf16_f32 v147, v162, v163
	global_store_dwordx4 v[124:125], v[144:147], off
	v_mov_b32_e32 v159, v117
	v_mov_b32_e32 v158, v116
	v_mov_b32_e32 v147, v115
	v_mov_b32_e32 v146, v114
	v_mov_b32_e32 v157, v121
	v_mov_b32_e32 v156, v120
	v_mov_b32_e32 v145, v119
	v_mov_b32_e32 v144, v118
	v_cvt_pk_bf16_f32 v114, v144, v145
	v_cvt_pk_bf16_f32 v115, v156, v157
	v_cvt_pk_bf16_f32 v116, v146, v147
	v_cvt_pk_bf16_f32 v117, v158, v159
	global_store_dwordx4 v[124:125], v[114:117], off offset:256
	v_mov_b32_e32 v121, v109
	v_mov_b32_e32 v120, v108
	v_mov_b32_e32 v117, v107
	v_mov_b32_e32 v116, v106
	v_mov_b32_e32 v119, v113
	v_mov_b32_e32 v118, v112
	v_mov_b32_e32 v115, v111
	v_mov_b32_e32 v114, v110
	v_or_b32_e32 v108, 16, v168
	v_mov_b64_e32 v[106:107], s[92:93]
	v_mad_i64_i32 v[106:107], s[24:25], v108, s80, v[106:107]
	v_lshl_add_u64 v[106:107], v[122:123], 1, v[106:107]
	v_cvt_pk_bf16_f32 v108, v114, v115
	v_cvt_pk_bf16_f32 v109, v118, v119
	v_cvt_pk_bf16_f32 v110, v116, v117
	v_cvt_pk_bf16_f32 v111, v120, v121
	global_store_dwordx4 v[106:107], v[108:111], off
	v_mov_b32_e32 v115, v101
	v_mov_b32_e32 v114, v100
	v_mov_b32_e32 v111, v99
	v_mov_b32_e32 v110, v98
	v_mov_b32_e32 v113, v105
	v_mov_b32_e32 v112, v104
	v_mov_b32_e32 v109, v103
	v_mov_b32_e32 v108, v102
	v_cvt_pk_bf16_f32 v98, v108, v109
	v_cvt_pk_bf16_f32 v99, v112, v113
	v_cvt_pk_bf16_f32 v100, v110, v111
	v_cvt_pk_bf16_f32 v101, v114, v115
	global_store_dwordx4 v[106:107], v[98:101], off offset:256
	v_mov_b32_e32 v105, v93
	v_mov_b32_e32 v104, v92
	v_mov_b32_e32 v101, v91
	v_mov_b32_e32 v100, v90
	v_mov_b32_e32 v103, v97
	v_mov_b32_e32 v102, v96
	v_mov_b32_e32 v99, v95
	v_mov_b32_e32 v98, v94
	v_or_b32_e32 v92, 32, v168
	v_mov_b64_e32 v[90:91], s[92:93]
	v_mad_i64_i32 v[90:91], s[24:25], v92, s80, v[90:91]
	v_lshl_add_u64 v[90:91], v[122:123], 1, v[90:91]
	v_cvt_pk_bf16_f32 v92, v98, v99
	v_cvt_pk_bf16_f32 v93, v102, v103
	v_cvt_pk_bf16_f32 v94, v100, v101
	v_cvt_pk_bf16_f32 v95, v104, v105
	global_store_dwordx4 v[90:91], v[92:95], off
	v_mov_b32_e32 v99, v85
	v_mov_b32_e32 v98, v84
	v_mov_b32_e32 v95, v83
	v_mov_b32_e32 v94, v82
	v_mov_b32_e32 v97, v89
	v_mov_b32_e32 v96, v88
	v_mov_b32_e32 v93, v87
	v_mov_b32_e32 v92, v86
	v_cvt_pk_bf16_f32 v82, v92, v93
	v_cvt_pk_bf16_f32 v83, v96, v97
	v_cvt_pk_bf16_f32 v84, v94, v95
	v_cvt_pk_bf16_f32 v85, v98, v99
	global_store_dwordx4 v[90:91], v[82:85], off offset:256
	v_mov_b32_e32 v89, v77
	v_mov_b32_e32 v88, v76
	v_mov_b32_e32 v85, v75
	v_mov_b32_e32 v84, v74
	v_mov_b32_e32 v87, v81
	v_mov_b32_e32 v86, v80
	v_mov_b32_e32 v83, v79
	v_mov_b32_e32 v82, v78
	v_or_b32_e32 v76, 48, v168
	v_mov_b64_e32 v[74:75], s[92:93]
	v_mad_i64_i32 v[74:75], s[24:25], v76, s80, v[74:75]
	v_lshl_add_u64 v[74:75], v[122:123], 1, v[74:75]
	v_cvt_pk_bf16_f32 v76, v82, v83
	v_cvt_pk_bf16_f32 v77, v86, v87
	v_cvt_pk_bf16_f32 v78, v84, v85
	v_cvt_pk_bf16_f32 v79, v88, v89
	global_store_dwordx4 v[74:75], v[76:79], off
	v_mov_b32_e32 v83, v69
	v_mov_b32_e32 v82, v68
	v_mov_b32_e32 v79, v67
	v_mov_b32_e32 v78, v66
	v_mov_b32_e32 v81, v73
	v_mov_b32_e32 v80, v72
	v_mov_b32_e32 v77, v71
	v_mov_b32_e32 v76, v70
	v_cvt_pk_bf16_f32 v66, v76, v77
	v_cvt_pk_bf16_f32 v67, v80, v81
	v_cvt_pk_bf16_f32 v68, v78, v79
	v_cvt_pk_bf16_f32 v69, v82, v83
	global_store_dwordx4 v[74:75], v[66:69], off offset:256
	v_mov_b32_e32 v73, v61
	v_mov_b32_e32 v72, v60
	v_mov_b32_e32 v69, v59
	v_mov_b32_e32 v68, v58
	v_mov_b32_e32 v71, v65
	v_mov_b32_e32 v70, v64
	v_mov_b32_e32 v67, v63
	v_mov_b32_e32 v66, v62
	v_add_u32_e32 v60, 0x80, v168
	v_mov_b64_e32 v[58:59], s[92:93]
	v_mad_i64_i32 v[58:59], s[24:25], v60, s80, v[58:59]
	v_lshl_add_u64 v[58:59], v[122:123], 1, v[58:59]
	v_cvt_pk_bf16_f32 v60, v66, v67
	v_cvt_pk_bf16_f32 v61, v70, v71
	v_cvt_pk_bf16_f32 v62, v68, v69
	v_cvt_pk_bf16_f32 v63, v72, v73
	global_store_dwordx4 v[58:59], v[60:63], off
	v_mov_b32_e32 v67, v53
	v_mov_b32_e32 v66, v52
	v_mov_b32_e32 v63, v51
	v_mov_b32_e32 v62, v50
	v_mov_b32_e32 v65, v57
	v_mov_b32_e32 v64, v56
	v_mov_b32_e32 v61, v55
	v_mov_b32_e32 v60, v54
	v_cvt_pk_bf16_f32 v50, v60, v61
	v_cvt_pk_bf16_f32 v51, v64, v65
	v_cvt_pk_bf16_f32 v52, v62, v63
	v_cvt_pk_bf16_f32 v53, v66, v67
	global_store_dwordx4 v[58:59], v[50:53], off offset:256
	v_mov_b32_e32 v57, v45
	v_mov_b32_e32 v56, v44
	v_mov_b32_e32 v53, v43
	v_mov_b32_e32 v52, v42
	v_mov_b32_e32 v55, v49
	v_mov_b32_e32 v54, v48
	v_mov_b32_e32 v51, v47
	v_mov_b32_e32 v50, v46
	v_add_u32_e32 v44, 0x90, v168
	v_mov_b64_e32 v[42:43], s[92:93]
	v_mad_i64_i32 v[42:43], s[24:25], v44, s80, v[42:43]
	v_lshl_add_u64 v[42:43], v[122:123], 1, v[42:43]
; __device__ __forceinline__ unsigned cvt_pk_bf16(float lo, float hi) { const f32x2e_t v = {lo, hi}; return __builtin_bit_cast(unsigned, __builtin_convertvector(v, bf16x2e_t)); }
; __device__ __forceinline__ float fsigmoid(float v) { return __builtin_amdgcn_rcpf(1.f + __expf(-v)); }
;     __device__ __forceinline__ void operator()(const f32x4 (&acc)[2][2][4][2], const Unit& u, int wr, int wc, int fr, int fq) const {
;     ...
;         for (int ai = 0; ai < 2; ++ai)
; #pragma unroll
;             for (int m = 0; m < 4; ++m) { bf16_t* rowp = Z + (size_t)(row0 + ai * HALF + m * 16) * ldz + col0;
; #pragma unroll
;                 for (int bj = 0; bj < 2; ++bj) { f32x4 v0 = acc[ai][bj][m][0], v1 = acc[ai][bj][m][1];
;                     if (mode == 1) { v0 = v0 * 0.18033688011112042f; v1 = v1 * 0.18033688011112042f; }
;                     else if (mode == 2) {
; #pragma unroll
;                         for (int j = 0; j < 4; ++j) { v0[j] = v0[j] * fsigmoid(v0[j]); v1[j] = v1[j] * fsigmoid(v1[j]); } }
;                     else if (mode == 3) {
; #pragma unroll
;                         for (int j = 0; j < 4; ++j) { v0[j] = fsigmoid(v0[j]); v1[j] = fsigmoid(v1[j]); } }
;                     u32x4 w; w.x = cvt_pk_bf16(v0[0], v0[1]); w.y = cvt_pk_bf16(v0[2], v0[3]); w.z = cvt_pk_bf16(v1[0], v1[1]); w.w = cvt_pk_bf16(v1[2], v1[3]);
;                     *(u32x4*)(rowp + bj * HALF) = w; } }
	v_cvt_pk_bf16_f32 v44, v50, v51
	v_cvt_pk_bf16_f32 v45, v54, v55
	v_cvt_pk_bf16_f32 v46, v52, v53
	v_cvt_pk_bf16_f32 v47, v56, v57
	global_store_dwordx4 v[42:43], v[44:47], off
	v_mov_b32_e32 v51, v37
	v_mov_b32_e32 v50, v36
	v_mov_b32_e32 v47, v35
	v_mov_b32_e32 v46, v34
	v_mov_b32_e32 v49, v41
	v_mov_b32_e32 v48, v40
	v_mov_b32_e32 v45, v39
	v_mov_b32_e32 v44, v38
	v_cvt_pk_bf16_f32 v34, v44, v45
	v_cvt_pk_bf16_f32 v35, v48, v49
	v_cvt_pk_bf16_f32 v36, v46, v47
	v_cvt_pk_bf16_f32 v37, v50, v51
	global_store_dwordx4 v[42:43], v[34:37], off offset:256
	v_mov_b32_e32 v41, v29
	v_mov_b32_e32 v40, v28
	v_mov_b32_e32 v37, v27
	v_mov_b32_e32 v36, v26
	v_mov_b32_e32 v39, v33
	v_mov_b32_e32 v38, v32
	v_mov_b32_e32 v35, v31
	v_mov_b32_e32 v34, v30
	v_add_u32_e32 v28, 0xa0, v168
	v_mov_b64_e32 v[26:27], s[92:93]
	v_mad_i64_i32 v[26:27], s[24:25], v28, s80, v[26:27]
	v_lshl_add_u64 v[26:27], v[122:123], 1, v[26:27]
	v_cvt_pk_bf16_f32 v28, v34, v35
	v_cvt_pk_bf16_f32 v29, v38, v39
	v_cvt_pk_bf16_f32 v30, v36, v37
	v_cvt_pk_bf16_f32 v31, v40, v41
	global_store_dwordx4 v[26:27], v[28:31], off
	v_mov_b32_e32 v35, v21
	v_mov_b32_e32 v34, v20
	v_mov_b32_e32 v31, v19
	v_mov_b32_e32 v30, v18
	v_mov_b32_e32 v33, v25
	v_mov_b32_e32 v32, v24
	v_mov_b32_e32 v29, v23
	v_mov_b32_e32 v28, v22
	v_cvt_pk_bf16_f32 v18, v28, v29
	v_cvt_pk_bf16_f32 v19, v32, v33
	v_cvt_pk_bf16_f32 v20, v30, v31
	v_cvt_pk_bf16_f32 v21, v34, v35
	global_store_dwordx4 v[26:27], v[18:21], off offset:256
	v_mov_b32_e32 v25, v13
	v_mov_b32_e32 v24, v12
	v_mov_b32_e32 v21, v11
	v_mov_b32_e32 v20, v10
	v_mov_b32_e32 v23, v17
	v_mov_b32_e32 v22, v16
	v_mov_b32_e32 v19, v15
	v_mov_b32_e32 v18, v14
	v_add_u32_e32 v12, 0xb0, v168
	v_mov_b64_e32 v[10:11], s[92:93]
	v_mad_i64_i32 v[10:11], s[24:25], v12, s80, v[10:11]
	v_lshl_add_u64 v[10:11], v[122:123], 1, v[10:11]
	v_cvt_pk_bf16_f32 v12, v18, v19
	v_cvt_pk_bf16_f32 v13, v22, v23
	v_cvt_pk_bf16_f32 v14, v20, v21
	v_cvt_pk_bf16_f32 v15, v24, v25
	global_store_dwordx4 v[10:11], v[12:15], off
	v_mov_b32_e32 v19, v5
	v_mov_b32_e32 v18, v4
	v_mov_b32_e32 v15, v3
	v_mov_b32_e32 v14, v2
	v_mov_b32_e32 v17, v9
	v_mov_b32_e32 v16, v8
	v_mov_b32_e32 v13, v7
	v_mov_b32_e32 v12, v6
	v_cvt_pk_bf16_f32 v2, v12, v13
	v_cvt_pk_bf16_f32 v3, v16, v17
	v_cvt_pk_bf16_f32 v4, v14, v15
	v_cvt_pk_bf16_f32 v5, v18, v19
	s_branch .Lepi_tail
.Lepi_class_1:
	s_mov_b32 s82, 0xca30000
	s_mov_b32 s83, 0x10a40000
	v_mul_f32_e32 v157, 0xbfb8aa3b, v122
	v_mul_f32_e32 v158, 0xbfb8aa3b, v145
	v_exp_f32_e32 v157, v157
	v_exp_f32_e32 v159, v158
	v_mul_f32_e32 v161, 0xbfb8aa3b, v124
	v_mul_f32_e32 v162, 0xbfb8aa3b, v147
	v_add_f32_e32 v157, 1.0, v157
	v_mul_f32_e32 v156, 0xbfb8aa3b, v144
	v_rcp_f32_e32 v158, v157
	v_add_f32_e32 v157, 1.0, v159
	v_mul_f32_e32 v159, 0xbfb8aa3b, v123
	v_mul_f32_e32 v160, 0xbfb8aa3b, v146
	v_exp_f32_e32 v161, v161
	v_exp_f32_e32 v163, v162
	v_mul_f32_e32 v162, 0xbfb8aa3b, v125
	v_exp_f32_e32 v156, v156
	v_exp_f32_e32 v159, v159
	v_exp_f32_e32 v160, v160
	v_exp_f32_e32 v168, v162
	v_add_f32_e32 v161, 1.0, v161
	v_add_f32_e32 v156, 1.0, v156
	v_add_f32_e32 v159, 1.0, v159
	v_add_f32_e32 v160, 1.0, v160
	v_rcp_f32_e32 v162, v161
	v_add_f32_e32 v161, 1.0, v163
	v_add_f32_e32 v163, 1.0, v168
	v_rcp_f32_e32 v156, v156
	v_rcp_f32_e32 v157, v157
	v_rcp_f32_e32 v160, v160
	v_rcp_f32_e32 v161, v161
	v_rcp_f32_e32 v163, v163
	v_rcp_f32_e32 v159, v159
	v_pk_mul_f32 v[156:157], v[144:145], v[156:157]
	v_pk_mul_f32 v[160:161], v[146:147], v[160:161]
	v_pk_mul_f32 v[162:163], v[124:125], v[162:163]
	v_pk_mul_f32 v[158:159], v[122:123], v[158:159]
	v_lshl_add_u32 v168, s27, 8, v164
	v_lshl_or_b32 v122, s26, 8, v166
	v_mov_b64_e32 v[124:125], s[92:93]
	v_ashrrev_i32_e32 v123, 31, v122
	v_mad_i64_i32 v[124:125], s[8:9], v168, s80, v[124:125]
	v_lshl_add_u64 v[124:125], v[122:123], 1, v[124:125]
	v_cvt_pk_bf16_f32 v144, v156, v157
	v_cvt_pk_bf16_f32 v145, v160, v161
	v_cvt_pk_bf16_f32 v146, v158, v159
	v_cvt_pk_bf16_f32 v147, v162, v163
	global_store_dwordx4 v[124:125], v[144:147], off
	s_nop 1
	v_mul_f32_e32 v145, 0xbfb8aa3b, v114
	v_mul_f32_e32 v146, 0xbfb8aa3b, v119
	v_exp_f32_e32 v145, v145
	v_exp_f32_e32 v147, v146
	v_mul_f32_e32 v157, 0xbfb8aa3b, v116
	v_mul_f32_e32 v158, 0xbfb8aa3b, v121
	v_add_f32_e32 v145, 1.0, v145
	v_mul_f32_e32 v144, 0xbfb8aa3b, v118
	v_rcp_f32_e32 v146, v145
	v_add_f32_e32 v145, 1.0, v147
	v_mul_f32_e32 v147, 0xbfb8aa3b, v115
	v_mul_f32_e32 v156, 0xbfb8aa3b, v120
	v_exp_f32_e32 v157, v157
	v_exp_f32_e32 v159, v158
	v_mul_f32_e32 v158, 0xbfb8aa3b, v117
	v_exp_f32_e32 v144, v144
	v_exp_f32_e32 v147, v147
	v_exp_f32_e32 v156, v156
	v_exp_f32_e32 v160, v158
	v_add_f32_e32 v157, 1.0, v157
	v_add_f32_e32 v144, 1.0, v144
	v_add_f32_e32 v147, 1.0, v147
	v_add_f32_e32 v156, 1.0, v156
	v_rcp_f32_e32 v158, v157
	v_add_f32_e32 v157, 1.0, v159
	v_add_f32_e32 v159, 1.0, v160
	v_rcp_f32_e32 v144, v144
	v_rcp_f32_e32 v145, v145
	v_rcp_f32_e32 v156, v156
	v_rcp_f32_e32 v157, v157
	v_rcp_f32_e32 v159, v159
	v_rcp_f32_e32 v147, v147
	v_pk_mul_f32 v[144:145], v[118:119], v[144:145]
	v_pk_mul_f32 v[156:157], v[120:121], v[156:157]
	v_pk_mul_f32 v[158:159], v[116:117], v[158:159]
	v_pk_mul_f32 v[146:147], v[114:115], v[146:147]
	v_cvt_pk_bf16_f32 v114, v144, v145
	v_cvt_pk_bf16_f32 v115, v156, v157
	v_cvt_pk_bf16_f32 v116, v146, v147
	v_cvt_pk_bf16_f32 v117, v158, v159
	global_store_dwordx4 v[124:125], v[114:117], off offset:256
	s_nop 1
	v_mul_f32_e32 v115, 0xbfb8aa3b, v106
	v_mul_f32_e32 v116, 0xbfb8aa3b, v111
	v_exp_f32_e32 v115, v115
	v_exp_f32_e32 v117, v116
	v_mul_f32_e32 v119, 0xbfb8aa3b, v108
	v_mul_f32_e32 v120, 0xbfb8aa3b, v113
	v_add_f32_e32 v115, 1.0, v115
; __device__ __forceinline__ unsigned cvt_pk_bf16(float lo, float hi) { const f32x2e_t v = {lo, hi}; return __builtin_bit_cast(unsigned, __builtin_convertvector(v, bf16x2e_t)); }
; __device__ __forceinline__ float fsigmoid(float v) { return __builtin_amdgcn_rcpf(1.f + __expf(-v)); }
;     __device__ __forceinline__ void operator()(const f32x4 (&acc)[2][2][4][2], const Unit& u, int wr, int wc, int fr, int fq) const {
;     ...
;         for (int ai = 0; ai < 2; ++ai)
; #pragma unroll
;             for (int m = 0; m < 4; ++m) { bf16_t* rowp = Z + (size_t)(row0 + ai * HALF + m * 16) * ldz + col0;
; #pragma unroll
;                 for (int bj = 0; bj < 2; ++bj) { f32x4 v0 = acc[ai][bj][m][0], v1 = acc[ai][bj][m][1];
;                     if (mode == 1) { v0 = v0 * 0.18033688011112042f; v1 = v1 * 0.18033688011112042f; }
;                     else if (mode == 2) {
; #pragma unroll
;                         for (int j = 0; j < 4; ++j) { v0[j] = v0[j] * fsigmoid(v0[j]); v1[j] = v1[j] * fsigmoid(v1[j]); } }
;                     else if (mode == 3) {
; #pragma unroll
;                         for (int j = 0; j < 4; ++j) { v0[j] = fsigmoid(v0[j]); v1[j] = fsigmoid(v1[j]); } }
;                     u32x4 w; w.x = cvt_pk_bf16(v0[0], v0[1]); w.y = cvt_pk_bf16(v0[2], v0[3]); w.z = cvt_pk_bf16(v1[0], v1[1]); w.w = cvt_pk_bf16(v1[2], v1[3]);
;                     *(u32x4*)(rowp + bj * HALF) = w; } }
	v_mul_f32_e32 v114, 0xbfb8aa3b, v110
	v_rcp_f32_e32 v116, v115
	v_add_f32_e32 v115, 1.0, v117
	v_mul_f32_e32 v117, 0xbfb8aa3b, v107
	v_mul_f32_e32 v118, 0xbfb8aa3b, v112
	v_exp_f32_e32 v119, v119
	v_exp_f32_e32 v121, v120
	v_mul_f32_e32 v120, 0xbfb8aa3b, v109
	v_exp_f32_e32 v114, v114
	v_exp_f32_e32 v117, v117
	v_exp_f32_e32 v118, v118
	v_exp_f32_e32 v124, v120
	v_add_f32_e32 v119, 1.0, v119
	v_add_f32_e32 v114, 1.0, v114
	v_add_f32_e32 v117, 1.0, v117
	v_add_f32_e32 v118, 1.0, v118
	v_rcp_f32_e32 v120, v119
	v_add_f32_e32 v119, 1.0, v121
	v_add_f32_e32 v121, 1.0, v124
	v_rcp_f32_e32 v114, v114
	v_rcp_f32_e32 v115, v115
	v_rcp_f32_e32 v118, v118
	v_rcp_f32_e32 v119, v119
	v_rcp_f32_e32 v121, v121
	v_rcp_f32_e32 v117, v117
	v_pk_mul_f32 v[114:115], v[110:111], v[114:115]
	v_pk_mul_f32 v[118:119], v[112:113], v[118:119]
	v_pk_mul_f32 v[120:121], v[108:109], v[120:121]
	v_pk_mul_f32 v[116:117], v[106:107], v[116:117]
	v_or_b32_e32 v108, 16, v168
	v_mov_b64_e32 v[106:107], s[92:93]
	v_mad_i64_i32 v[106:107], s[24:25], v108, s80, v[106:107]
	v_lshl_add_u64 v[106:107], v[122:123], 1, v[106:107]
	v_cvt_pk_bf16_f32 v108, v114, v115
	v_cvt_pk_bf16_f32 v109, v118, v119
	v_cvt_pk_bf16_f32 v110, v116, v117
	v_cvt_pk_bf16_f32 v111, v120, v121
	global_store_dwordx4 v[106:107], v[108:111], off
	s_nop 1
	v_mul_f32_e32 v109, 0xbfb8aa3b, v98
	v_mul_f32_e32 v110, 0xbfb8aa3b, v103
	v_exp_f32_e32 v109, v109
	v_exp_f32_e32 v111, v110
	v_mul_f32_e32 v113, 0xbfb8aa3b, v100
	v_mul_f32_e32 v114, 0xbfb8aa3b, v105
	v_add_f32_e32 v109, 1.0, v109
	v_mul_f32_e32 v108, 0xbfb8aa3b, v102
	v_rcp_f32_e32 v110, v109
	v_add_f32_e32 v109, 1.0, v111
	v_mul_f32_e32 v111, 0xbfb8aa3b, v99
	v_mul_f32_e32 v112, 0xbfb8aa3b, v104
	v_exp_f32_e32 v113, v113
	v_exp_f32_e32 v115, v114
	v_mul_f32_e32 v114, 0xbfb8aa3b, v101
	v_exp_f32_e32 v108, v108
	v_exp_f32_e32 v111, v111
	v_exp_f32_e32 v112, v112
	v_exp_f32_e32 v116, v114
	v_add_f32_e32 v113, 1.0, v113
	v_add_f32_e32 v108, 1.0, v108
	v_add_f32_e32 v111, 1.0, v111
	v_add_f32_e32 v112, 1.0, v112
	v_rcp_f32_e32 v114, v113
	v_add_f32_e32 v113, 1.0, v115
	v_add_f32_e32 v115, 1.0, v116
	v_rcp_f32_e32 v108, v108
	v_rcp_f32_e32 v109, v109
	v_rcp_f32_e32 v112, v112
	v_rcp_f32_e32 v113, v113
	v_rcp_f32_e32 v115, v115
	v_rcp_f32_e32 v111, v111
	v_pk_mul_f32 v[108:109], v[102:103], v[108:109]
	v_pk_mul_f32 v[112:113], v[104:105], v[112:113]
	v_pk_mul_f32 v[114:115], v[100:101], v[114:115]
	v_pk_mul_f32 v[110:111], v[98:99], v[110:111]
	v_cvt_pk_bf16_f32 v98, v108, v109
	v_cvt_pk_bf16_f32 v99, v112, v113
	v_cvt_pk_bf16_f32 v100, v110, v111
	v_cvt_pk_bf16_f32 v101, v114, v115
	global_store_dwordx4 v[106:107], v[98:101], off offset:256
	s_nop 1
	v_mul_f32_e32 v99, 0xbfb8aa3b, v90
	v_mul_f32_e32 v100, 0xbfb8aa3b, v95
	v_exp_f32_e32 v99, v99
	v_exp_f32_e32 v101, v100
	v_mul_f32_e32 v103, 0xbfb8aa3b, v92
	v_mul_f32_e32 v104, 0xbfb8aa3b, v97
	v_add_f32_e32 v99, 1.0, v99
	v_mul_f32_e32 v98, 0xbfb8aa3b, v94
	v_rcp_f32_e32 v100, v99
	v_add_f32_e32 v99, 1.0, v101
	v_mul_f32_e32 v101, 0xbfb8aa3b, v91
	v_mul_f32_e32 v102, 0xbfb8aa3b, v96
	v_exp_f32_e32 v103, v103
	v_exp_f32_e32 v105, v104
	v_mul_f32_e32 v104, 0xbfb8aa3b, v93
	v_exp_f32_e32 v98, v98
	v_exp_f32_e32 v101, v101
	v_exp_f32_e32 v102, v102
	v_exp_f32_e32 v106, v104
	v_add_f32_e32 v103, 1.0, v103
	v_add_f32_e32 v98, 1.0, v98
	v_add_f32_e32 v101, 1.0, v101
	v_add_f32_e32 v102, 1.0, v102
	v_rcp_f32_e32 v104, v103
	v_add_f32_e32 v103, 1.0, v105
	v_add_f32_e32 v105, 1.0, v106
	v_rcp_f32_e32 v98, v98
	v_rcp_f32_e32 v99, v99
	v_rcp_f32_e32 v102, v102
	v_rcp_f32_e32 v103, v103
	v_rcp_f32_e32 v105, v105
	v_rcp_f32_e32 v101, v101
	v_pk_mul_f32 v[98:99], v[94:95], v[98:99]
	v_pk_mul_f32 v[102:103], v[96:97], v[102:103]
	v_pk_mul_f32 v[104:105], v[92:93], v[104:105]
	v_pk_mul_f32 v[100:101], v[90:91], v[100:101]
	v_or_b32_e32 v92, 32, v168
	v_mov_b64_e32 v[90:91], s[92:93]
	v_mad_i64_i32 v[90:91], s[24:25], v92, s80, v[90:91]
	v_lshl_add_u64 v[90:91], v[122:123], 1, v[90:91]
	v_cvt_pk_bf16_f32 v92, v98, v99
	v_cvt_pk_bf16_f32 v93, v102, v103
	v_cvt_pk_bf16_f32 v94, v100, v101
	v_cvt_pk_bf16_f32 v95, v104, v105
	global_store_dwordx4 v[90:91], v[92:95], off
	s_nop 1
	v_mul_f32_e32 v93, 0xbfb8aa3b, v82
	v_mul_f32_e32 v94, 0xbfb8aa3b, v87
	v_exp_f32_e32 v93, v93
	v_exp_f32_e32 v95, v94
	v_mul_f32_e32 v97, 0xbfb8aa3b, v84
	v_mul_f32_e32 v98, 0xbfb8aa3b, v89
	v_add_f32_e32 v93, 1.0, v93
	v_mul_f32_e32 v92, 0xbfb8aa3b, v86
	v_rcp_f32_e32 v94, v93
	v_add_f32_e32 v93, 1.0, v95
	v_mul_f32_e32 v95, 0xbfb8aa3b, v83
	v_mul_f32_e32 v96, 0xbfb8aa3b, v88
	v_exp_f32_e32 v97, v97
	v_exp_f32_e32 v99, v98
	v_mul_f32_e32 v98, 0xbfb8aa3b, v85
	v_exp_f32_e32 v92, v92
	v_exp_f32_e32 v95, v95
	v_exp_f32_e32 v96, v96
	v_exp_f32_e32 v100, v98
	v_add_f32_e32 v97, 1.0, v97
	v_add_f32_e32 v92, 1.0, v92
	v_add_f32_e32 v95, 1.0, v95
	v_add_f32_e32 v96, 1.0, v96
	v_rcp_f32_e32 v98, v97
	v_add_f32_e32 v97, 1.0, v99
	v_add_f32_e32 v99, 1.0, v100
	v_rcp_f32_e32 v92, v92
	v_rcp_f32_e32 v93, v93
	v_rcp_f32_e32 v96, v96
	v_rcp_f32_e32 v97, v97
	v_rcp_f32_e32 v99, v99
	v_rcp_f32_e32 v95, v95
	v_pk_mul_f32 v[92:93], v[86:87], v[92:93]
	v_pk_mul_f32 v[96:97], v[88:89], v[96:97]
	v_pk_mul_f32 v[98:99], v[84:85], v[98:99]
	v_pk_mul_f32 v[94:95], v[82:83], v[94:95]
	v_cvt_pk_bf16_f32 v82, v92, v93
	v_cvt_pk_bf16_f32 v83, v96, v97
	v_cvt_pk_bf16_f32 v84, v94, v95
	v_cvt_pk_bf16_f32 v85, v98, v99
	global_store_dwordx4 v[90:91], v[82:85], off offset:256
	s_nop 1
	v_mul_f32_e32 v83, 0xbfb8aa3b, v74
	v_mul_f32_e32 v84, 0xbfb8aa3b, v79
	v_exp_f32_e32 v83, v83
	v_exp_f32_e32 v85, v84
	v_mul_f32_e32 v87, 0xbfb8aa3b, v76
	v_mul_f32_e32 v88, 0xbfb8aa3b, v81
; __device__ __forceinline__ unsigned cvt_pk_bf16(float lo, float hi) { const f32x2e_t v = {lo, hi}; return __builtin_bit_cast(unsigned, __builtin_convertvector(v, bf16x2e_t)); }
; __device__ __forceinline__ float fsigmoid(float v) { return __builtin_amdgcn_rcpf(1.f + __expf(-v)); }
;     __device__ __forceinline__ void operator()(const f32x4 (&acc)[2][2][4][2], const Unit& u, int wr, int wc, int fr, int fq) const {
;     ...
;         for (int ai = 0; ai < 2; ++ai)
; #pragma unroll
;             for (int m = 0; m < 4; ++m) { bf16_t* rowp = Z + (size_t)(row0 + ai * HALF + m * 16) * ldz + col0;
; #pragma unroll
;                 for (int bj = 0; bj < 2; ++bj) { f32x4 v0 = acc[ai][bj][m][0], v1 = acc[ai][bj][m][1];
;                     if (mode == 1) { v0 = v0 * 0.18033688011112042f; v1 = v1 * 0.18033688011112042f; }
;                     else if (mode == 2) {
; #pragma unroll
;                         for (int j = 0; j < 4; ++j) { v0[j] = v0[j] * fsigmoid(v0[j]); v1[j] = v1[j] * fsigmoid(v1[j]); } }
;                     else if (mode == 3) {
; #pragma unroll
;                         for (int j = 0; j < 4; ++j) { v0[j] = fsigmoid(v0[j]); v1[j] = fsigmoid(v1[j]); } }
;                     u32x4 w; w.x = cvt_pk_bf16(v0[0], v0[1]); w.y = cvt_pk_bf16(v0[2], v0[3]); w.z = cvt_pk_bf16(v1[0], v1[1]); w.w = cvt_pk_bf16(v1[2], v1[3]);
;                     *(u32x4*)(rowp + bj * HALF) = w; } }
	v_add_f32_e32 v83, 1.0, v83
	v_mul_f32_e32 v82, 0xbfb8aa3b, v78
	v_rcp_f32_e32 v84, v83
	v_add_f32_e32 v83, 1.0, v85
	v_mul_f32_e32 v85, 0xbfb8aa3b, v75
	v_mul_f32_e32 v86, 0xbfb8aa3b, v80
	v_exp_f32_e32 v87, v87
	v_exp_f32_e32 v89, v88
	v_mul_f32_e32 v88, 0xbfb8aa3b, v77
	v_exp_f32_e32 v82, v82
	v_exp_f32_e32 v85, v85
	v_exp_f32_e32 v86, v86
	v_exp_f32_e32 v90, v88
	v_add_f32_e32 v87, 1.0, v87
	v_add_f32_e32 v82, 1.0, v82
	v_add_f32_e32 v85, 1.0, v85
	v_add_f32_e32 v86, 1.0, v86
	v_rcp_f32_e32 v88, v87
	v_add_f32_e32 v87, 1.0, v89
	v_add_f32_e32 v89, 1.0, v90
	v_rcp_f32_e32 v82, v82
	v_rcp_f32_e32 v83, v83
	v_rcp_f32_e32 v86, v86
	v_rcp_f32_e32 v87, v87
	v_rcp_f32_e32 v89, v89
	v_rcp_f32_e32 v85, v85
	v_pk_mul_f32 v[82:83], v[78:79], v[82:83]
	v_pk_mul_f32 v[86:87], v[80:81], v[86:87]
	v_pk_mul_f32 v[88:89], v[76:77], v[88:89]
	v_pk_mul_f32 v[84:85], v[74:75], v[84:85]
	v_or_b32_e32 v76, 48, v168
	v_mov_b64_e32 v[74:75], s[92:93]
	v_mad_i64_i32 v[74:75], s[24:25], v76, s80, v[74:75]
	v_lshl_add_u64 v[74:75], v[122:123], 1, v[74:75]
	v_cvt_pk_bf16_f32 v76, v82, v83
	v_cvt_pk_bf16_f32 v77, v86, v87
	v_cvt_pk_bf16_f32 v78, v84, v85
	v_cvt_pk_bf16_f32 v79, v88, v89
	global_store_dwordx4 v[74:75], v[76:79], off
	s_nop 1
	v_mul_f32_e32 v77, 0xbfb8aa3b, v66
	v_mul_f32_e32 v78, 0xbfb8aa3b, v71
	v_exp_f32_e32 v77, v77
	v_exp_f32_e32 v79, v78
	v_mul_f32_e32 v81, 0xbfb8aa3b, v68
	v_mul_f32_e32 v82, 0xbfb8aa3b, v73
	v_add_f32_e32 v77, 1.0, v77
	v_mul_f32_e32 v76, 0xbfb8aa3b, v70
	v_rcp_f32_e32 v78, v77
	v_add_f32_e32 v77, 1.0, v79
	v_mul_f32_e32 v79, 0xbfb8aa3b, v67
	v_mul_f32_e32 v80, 0xbfb8aa3b, v72
	v_exp_f32_e32 v81, v81
	v_exp_f32_e32 v83, v82
	v_mul_f32_e32 v82, 0xbfb8aa3b, v69
	v_exp_f32_e32 v76, v76
	v_exp_f32_e32 v79, v79
	v_exp_f32_e32 v80, v80
	v_exp_f32_e32 v84, v82
	v_add_f32_e32 v81, 1.0, v81
	v_add_f32_e32 v76, 1.0, v76
	v_add_f32_e32 v79, 1.0, v79
	v_add_f32_e32 v80, 1.0, v80
	v_rcp_f32_e32 v82, v81
	v_add_f32_e32 v81, 1.0, v83
	v_add_f32_e32 v83, 1.0, v84
	v_rcp_f32_e32 v76, v76
	v_rcp_f32_e32 v77, v77
	v_rcp_f32_e32 v80, v80
	v_rcp_f32_e32 v81, v81
	v_rcp_f32_e32 v83, v83
	v_rcp_f32_e32 v79, v79
	v_pk_mul_f32 v[76:77], v[70:71], v[76:77]
	v_pk_mul_f32 v[80:81], v[72:73], v[80:81]
	v_pk_mul_f32 v[82:83], v[68:69], v[82:83]
	v_pk_mul_f32 v[78:79], v[66:67], v[78:79]
	v_cvt_pk_bf16_f32 v66, v76, v77
	v_cvt_pk_bf16_f32 v67, v80, v81
	v_cvt_pk_bf16_f32 v68, v78, v79
	v_cvt_pk_bf16_f32 v69, v82, v83
	global_store_dwordx4 v[74:75], v[66:69], off offset:256
	s_nop 1
	v_mul_f32_e32 v67, 0xbfb8aa3b, v58
	v_mul_f32_e32 v68, 0xbfb8aa3b, v63
	v_exp_f32_e32 v67, v67
	v_exp_f32_e32 v69, v68
	v_mul_f32_e32 v71, 0xbfb8aa3b, v60
	v_mul_f32_e32 v72, 0xbfb8aa3b, v65
	v_add_f32_e32 v67, 1.0, v67
	v_mul_f32_e32 v66, 0xbfb8aa3b, v62
	v_rcp_f32_e32 v68, v67
	v_add_f32_e32 v67, 1.0, v69
	v_mul_f32_e32 v69, 0xbfb8aa3b, v59
	v_mul_f32_e32 v70, 0xbfb8aa3b, v64
	v_exp_f32_e32 v71, v71
	v_exp_f32_e32 v73, v72
	v_mul_f32_e32 v72, 0xbfb8aa3b, v61
	v_exp_f32_e32 v66, v66
	v_exp_f32_e32 v69, v69
	v_exp_f32_e32 v70, v70
	v_exp_f32_e32 v74, v72
	v_add_f32_e32 v71, 1.0, v71
	v_add_f32_e32 v66, 1.0, v66
	v_add_f32_e32 v69, 1.0, v69
	v_add_f32_e32 v70, 1.0, v70
	v_rcp_f32_e32 v72, v71
	v_add_f32_e32 v71, 1.0, v73
	v_add_f32_e32 v73, 1.0, v74
	v_rcp_f32_e32 v66, v66
	v_rcp_f32_e32 v67, v67
	v_rcp_f32_e32 v70, v70
	v_rcp_f32_e32 v71, v71
	v_rcp_f32_e32 v73, v73
	v_rcp_f32_e32 v69, v69
	v_pk_mul_f32 v[66:67], v[62:63], v[66:67]
	v_pk_mul_f32 v[70:71], v[64:65], v[70:71]
	v_pk_mul_f32 v[72:73], v[60:61], v[72:73]
	v_pk_mul_f32 v[68:69], v[58:59], v[68:69]
	v_add_u32_e32 v60, 0x80, v168
	v_mov_b64_e32 v[58:59], s[92:93]
	v_mad_i64_i32 v[58:59], s[24:25], v60, s80, v[58:59]
	v_lshl_add_u64 v[58:59], v[122:123], 1, v[58:59]
	v_cvt_pk_bf16_f32 v60, v66, v67
	v_cvt_pk_bf16_f32 v61, v70, v71
	v_cvt_pk_bf16_f32 v62, v68, v69
	v_cvt_pk_bf16_f32 v63, v72, v73
	global_store_dwordx4 v[58:59], v[60:63], off
	s_nop 1
	v_mul_f32_e32 v61, 0xbfb8aa3b, v50
	v_mul_f32_e32 v62, 0xbfb8aa3b, v55
	v_exp_f32_e32 v61, v61
	v_exp_f32_e32 v63, v62
	v_mul_f32_e32 v65, 0xbfb8aa3b, v52
	v_mul_f32_e32 v66, 0xbfb8aa3b, v57
	v_add_f32_e32 v61, 1.0, v61
	v_mul_f32_e32 v60, 0xbfb8aa3b, v54
	v_rcp_f32_e32 v62, v61
	v_add_f32_e32 v61, 1.0, v63
	v_mul_f32_e32 v63, 0xbfb8aa3b, v51
	v_mul_f32_e32 v64, 0xbfb8aa3b, v56
	v_exp_f32_e32 v65, v65
	v_exp_f32_e32 v67, v66
	v_mul_f32_e32 v66, 0xbfb8aa3b, v53
	v_exp_f32_e32 v60, v60
	v_exp_f32_e32 v63, v63
	v_exp_f32_e32 v64, v64
	v_exp_f32_e32 v68, v66
	v_add_f32_e32 v65, 1.0, v65
	v_add_f32_e32 v60, 1.0, v60
	v_add_f32_e32 v63, 1.0, v63
	v_add_f32_e32 v64, 1.0, v64
	v_rcp_f32_e32 v66, v65
	v_add_f32_e32 v65, 1.0, v67
	v_add_f32_e32 v67, 1.0, v68
	v_rcp_f32_e32 v60, v60
	v_rcp_f32_e32 v61, v61
	v_rcp_f32_e32 v64, v64
	v_rcp_f32_e32 v65, v65
	v_rcp_f32_e32 v67, v67
	v_rcp_f32_e32 v63, v63
	v_pk_mul_f32 v[60:61], v[54:55], v[60:61]
	v_pk_mul_f32 v[64:65], v[56:57], v[64:65]
	v_pk_mul_f32 v[66:67], v[52:53], v[66:67]
	v_pk_mul_f32 v[62:63], v[50:51], v[62:63]
	v_cvt_pk_bf16_f32 v50, v60, v61
	v_cvt_pk_bf16_f32 v51, v64, v65
	v_cvt_pk_bf16_f32 v52, v62, v63
	v_cvt_pk_bf16_f32 v53, v66, v67
	global_store_dwordx4 v[58:59], v[50:53], off offset:256
	s_nop 1
	v_mul_f32_e32 v51, 0xbfb8aa3b, v42
	v_mul_f32_e32 v52, 0xbfb8aa3b, v47
	v_exp_f32_e32 v51, v51
	v_exp_f32_e32 v53, v52
	v_mul_f32_e32 v55, 0xbfb8aa3b, v44
	v_mul_f32_e32 v56, 0xbfb8aa3b, v49
	v_add_f32_e32 v51, 1.0, v51
	v_mul_f32_e32 v50, 0xbfb8aa3b, v46
	v_rcp_f32_e32 v52, v51
	v_add_f32_e32 v51, 1.0, v53
	v_mul_f32_e32 v53, 0xbfb8aa3b, v43
	v_mul_f32_e32 v54, 0xbfb8aa3b, v48
	v_exp_f32_e32 v55, v55
	v_exp_f32_e32 v57, v56
; __device__ __forceinline__ unsigned cvt_pk_bf16(float lo, float hi) { const f32x2e_t v = {lo, hi}; return __builtin_bit_cast(unsigned, __builtin_convertvector(v, bf16x2e_t)); }
; __device__ __forceinline__ float fsigmoid(float v) { return __builtin_amdgcn_rcpf(1.f + __expf(-v)); }
;     __device__ __forceinline__ void operator()(const f32x4 (&acc)[2][2][4][2], const Unit& u, int wr, int wc, int fr, int fq) const {
;     ...
;             for (int m = 0; m < 4; ++m) { bf16_t* rowp = Z + (size_t)(row0 + ai * HALF + m * 16) * ldz + col0;
; #pragma unroll
;                 for (int bj = 0; bj < 2; ++bj) { f32x4 v0 = acc[ai][bj][m][0], v1 = acc[ai][bj][m][1];
;                     if (mode == 1) { v0 = v0 * 0.18033688011112042f; v1 = v1 * 0.18033688011112042f; }
;                     else if (mode == 2) {
; #pragma unroll
;                         for (int j = 0; j < 4; ++j) { v0[j] = v0[j] * fsigmoid(v0[j]); v1[j] = v1[j] * fsigmoid(v1[j]); } }
;                     else if (mode == 3) {
; #pragma unroll
;                         for (int j = 0; j < 4; ++j) { v0[j] = fsigmoid(v0[j]); v1[j] = fsigmoid(v1[j]); } }
;                     u32x4 w; w.x = cvt_pk_bf16(v0[0], v0[1]); w.y = cvt_pk_bf16(v0[2], v0[3]); w.z = cvt_pk_bf16(v1[0], v1[1]); w.w = cvt_pk_bf16(v1[2], v1[3]);
;                     *(u32x4*)(rowp + bj * HALF) = w; } }
	v_mul_f32_e32 v56, 0xbfb8aa3b, v45
	v_exp_f32_e32 v50, v50
	v_exp_f32_e32 v53, v53
	v_exp_f32_e32 v54, v54
	v_exp_f32_e32 v58, v56
	v_add_f32_e32 v55, 1.0, v55
	v_add_f32_e32 v50, 1.0, v50
	v_add_f32_e32 v53, 1.0, v53
	v_add_f32_e32 v54, 1.0, v54
	v_rcp_f32_e32 v56, v55
	v_add_f32_e32 v55, 1.0, v57
	v_add_f32_e32 v57, 1.0, v58
	v_rcp_f32_e32 v50, v50
	v_rcp_f32_e32 v51, v51
	v_rcp_f32_e32 v54, v54
	v_rcp_f32_e32 v55, v55
	v_rcp_f32_e32 v57, v57
	v_rcp_f32_e32 v53, v53
	v_pk_mul_f32 v[50:51], v[46:47], v[50:51]
	v_pk_mul_f32 v[54:55], v[48:49], v[54:55]
	v_pk_mul_f32 v[56:57], v[44:45], v[56:57]
	v_pk_mul_f32 v[52:53], v[42:43], v[52:53]
	v_add_u32_e32 v44, 0x90, v168
	v_mov_b64_e32 v[42:43], s[92:93]
	v_mad_i64_i32 v[42:43], s[24:25], v44, s80, v[42:43]
	v_lshl_add_u64 v[42:43], v[122:123], 1, v[42:43]
	v_cvt_pk_bf16_f32 v44, v50, v51
	v_cvt_pk_bf16_f32 v45, v54, v55
	v_cvt_pk_bf16_f32 v46, v52, v53
	v_cvt_pk_bf16_f32 v47, v56, v57
	global_store_dwordx4 v[42:43], v[44:47], off
	s_nop 1
	v_mul_f32_e32 v45, 0xbfb8aa3b, v34
	v_mul_f32_e32 v46, 0xbfb8aa3b, v39
	v_exp_f32_e32 v45, v45
	v_exp_f32_e32 v47, v46
	v_mul_f32_e32 v49, 0xbfb8aa3b, v36
	v_mul_f32_e32 v50, 0xbfb8aa3b, v41
	v_add_f32_e32 v45, 1.0, v45
	v_mul_f32_e32 v44, 0xbfb8aa3b, v38
	v_rcp_f32_e32 v46, v45
	v_add_f32_e32 v45, 1.0, v47
	v_mul_f32_e32 v47, 0xbfb8aa3b, v35
	v_mul_f32_e32 v48, 0xbfb8aa3b, v40
	v_exp_f32_e32 v49, v49
	v_exp_f32_e32 v51, v50
	v_mul_f32_e32 v50, 0xbfb8aa3b, v37
	v_exp_f32_e32 v44, v44
	v_exp_f32_e32 v47, v47
	v_exp_f32_e32 v48, v48
	v_exp_f32_e32 v52, v50
	v_add_f32_e32 v49, 1.0, v49
	v_add_f32_e32 v44, 1.0, v44
	v_add_f32_e32 v47, 1.0, v47
	v_add_f32_e32 v48, 1.0, v48
	v_rcp_f32_e32 v50, v49
	v_add_f32_e32 v49, 1.0, v51
	v_add_f32_e32 v51, 1.0, v52
	v_rcp_f32_e32 v44, v44
	v_rcp_f32_e32 v45, v45
	v_rcp_f32_e32 v48, v48
	v_rcp_f32_e32 v49, v49
	v_rcp_f32_e32 v51, v51
	v_rcp_f32_e32 v47, v47
	v_pk_mul_f32 v[44:45], v[38:39], v[44:45]
	v_pk_mul_f32 v[48:49], v[40:41], v[48:49]
	v_pk_mul_f32 v[50:51], v[36:37], v[50:51]
	v_pk_mul_f32 v[46:47], v[34:35], v[46:47]
	v_cvt_pk_bf16_f32 v34, v44, v45
	v_cvt_pk_bf16_f32 v35, v48, v49
	v_cvt_pk_bf16_f32 v36, v46, v47
	v_cvt_pk_bf16_f32 v37, v50, v51
	global_store_dwordx4 v[42:43], v[34:37], off offset:256
	s_nop 1
	v_mul_f32_e32 v35, 0xbfb8aa3b, v26
	v_mul_f32_e32 v36, 0xbfb8aa3b, v31
	v_exp_f32_e32 v35, v35
	v_exp_f32_e32 v37, v36
	v_mul_f32_e32 v39, 0xbfb8aa3b, v28
	v_mul_f32_e32 v40, 0xbfb8aa3b, v33
	v_add_f32_e32 v35, 1.0, v35
	v_mul_f32_e32 v34, 0xbfb8aa3b, v30
	v_rcp_f32_e32 v36, v35
	v_add_f32_e32 v35, 1.0, v37
	v_mul_f32_e32 v37, 0xbfb8aa3b, v27
	v_mul_f32_e32 v38, 0xbfb8aa3b, v32
	v_exp_f32_e32 v39, v39
	v_exp_f32_e32 v41, v40
	v_mul_f32_e32 v40, 0xbfb8aa3b, v29
	v_exp_f32_e32 v34, v34
	v_exp_f32_e32 v37, v37
	v_exp_f32_e32 v38, v38
	v_exp_f32_e32 v42, v40
	v_add_f32_e32 v39, 1.0, v39
	v_add_f32_e32 v34, 1.0, v34
	v_add_f32_e32 v37, 1.0, v37
	v_add_f32_e32 v38, 1.0, v38
	v_rcp_f32_e32 v40, v39
	v_add_f32_e32 v39, 1.0, v41
	v_add_f32_e32 v41, 1.0, v42
	v_rcp_f32_e32 v34, v34
	v_rcp_f32_e32 v35, v35
	v_rcp_f32_e32 v38, v38
	v_rcp_f32_e32 v39, v39
	v_rcp_f32_e32 v41, v41
	v_rcp_f32_e32 v37, v37
	v_pk_mul_f32 v[34:35], v[30:31], v[34:35]
	v_pk_mul_f32 v[38:39], v[32:33], v[38:39]
	v_pk_mul_f32 v[40:41], v[28:29], v[40:41]
	v_pk_mul_f32 v[36:37], v[26:27], v[36:37]
	v_add_u32_e32 v28, 0xa0, v168
	v_mov_b64_e32 v[26:27], s[92:93]
	v_mad_i64_i32 v[26:27], s[24:25], v28, s80, v[26:27]
	v_lshl_add_u64 v[26:27], v[122:123], 1, v[26:27]
	v_cvt_pk_bf16_f32 v28, v34, v35
	v_cvt_pk_bf16_f32 v29, v38, v39
	v_cvt_pk_bf16_f32 v30, v36, v37
	v_cvt_pk_bf16_f32 v31, v40, v41
	global_store_dwordx4 v[26:27], v[28:31], off
	s_nop 1
	v_mul_f32_e32 v29, 0xbfb8aa3b, v18
	v_mul_f32_e32 v30, 0xbfb8aa3b, v23
	v_exp_f32_e32 v29, v29
	v_exp_f32_e32 v31, v30
	v_mul_f32_e32 v33, 0xbfb8aa3b, v20
	v_mul_f32_e32 v34, 0xbfb8aa3b, v25
	v_add_f32_e32 v29, 1.0, v29
	v_mul_f32_e32 v28, 0xbfb8aa3b, v22
	v_rcp_f32_e32 v30, v29
	v_add_f32_e32 v29, 1.0, v31
	v_mul_f32_e32 v31, 0xbfb8aa3b, v19
	v_mul_f32_e32 v32, 0xbfb8aa3b, v24
	v_exp_f32_e32 v33, v33
	v_exp_f32_e32 v35, v34
	v_mul_f32_e32 v34, 0xbfb8aa3b, v21
	v_exp_f32_e32 v28, v28
	v_exp_f32_e32 v31, v31
	v_exp_f32_e32 v32, v32
	v_exp_f32_e32 v36, v34
	v_add_f32_e32 v33, 1.0, v33
	v_add_f32_e32 v28, 1.0, v28
	v_add_f32_e32 v31, 1.0, v31
	v_add_f32_e32 v32, 1.0, v32
	v_rcp_f32_e32 v34, v33
	v_add_f32_e32 v33, 1.0, v35
	v_add_f32_e32 v35, 1.0, v36
	v_rcp_f32_e32 v28, v28
	v_rcp_f32_e32 v29, v29
	v_rcp_f32_e32 v32, v32
	v_rcp_f32_e32 v33, v33
	v_rcp_f32_e32 v35, v35
	v_rcp_f32_e32 v31, v31
	v_pk_mul_f32 v[28:29], v[22:23], v[28:29]
	v_pk_mul_f32 v[32:33], v[24:25], v[32:33]
	v_pk_mul_f32 v[34:35], v[20:21], v[34:35]
	v_pk_mul_f32 v[30:31], v[18:19], v[30:31]
	v_cvt_pk_bf16_f32 v18, v28, v29
	v_cvt_pk_bf16_f32 v19, v32, v33
	v_cvt_pk_bf16_f32 v20, v30, v31
	v_cvt_pk_bf16_f32 v21, v34, v35
	global_store_dwordx4 v[26:27], v[18:21], off offset:256
	s_nop 1
	v_mul_f32_e32 v19, 0xbfb8aa3b, v10
	v_mul_f32_e32 v20, 0xbfb8aa3b, v15
	v_exp_f32_e32 v19, v19
	v_exp_f32_e32 v21, v20
	v_mul_f32_e32 v23, 0xbfb8aa3b, v12
	v_mul_f32_e32 v24, 0xbfb8aa3b, v17
	v_add_f32_e32 v19, 1.0, v19
	v_mul_f32_e32 v18, 0xbfb8aa3b, v14
	v_rcp_f32_e32 v20, v19
	v_add_f32_e32 v19, 1.0, v21
	v_mul_f32_e32 v21, 0xbfb8aa3b, v11
	v_mul_f32_e32 v22, 0xbfb8aa3b, v16
	v_exp_f32_e32 v23, v23
	v_exp_f32_e32 v25, v24
	v_mul_f32_e32 v24, 0xbfb8aa3b, v13
	v_exp_f32_e32 v18, v18
	v_exp_f32_e32 v21, v21
	v_exp_f32_e32 v22, v22
	v_exp_f32_e32 v26, v24
	v_add_f32_e32 v23, 1.0, v23
	v_add_f32_e32 v18, 1.0, v18
	v_add_f32_e32 v21, 1.0, v21
; __device__ __forceinline__ unsigned cvt_pk_bf16(float lo, float hi) { const f32x2e_t v = {lo, hi}; return __builtin_bit_cast(unsigned, __builtin_convertvector(v, bf16x2e_t)); }
; __device__ __forceinline__ float fsigmoid(float v) { return __builtin_amdgcn_rcpf(1.f + __expf(-v)); }
;     __device__ __forceinline__ void operator()(const f32x4 (&acc)[2][2][4][2], const Unit& u, int wr, int wc, int fr, int fq) const {
;     ...
;             for (int m = 0; m < 4; ++m) { bf16_t* rowp = Z + (size_t)(row0 + ai * HALF + m * 16) * ldz + col0;
; #pragma unroll
;                 for (int bj = 0; bj < 2; ++bj) { f32x4 v0 = acc[ai][bj][m][0], v1 = acc[ai][bj][m][1];
;                     if (mode == 1) { v0 = v0 * 0.18033688011112042f; v1 = v1 * 0.18033688011112042f; }
;                     else if (mode == 2) {
; #pragma unroll
;                         for (int j = 0; j < 4; ++j) { v0[j] = v0[j] * fsigmoid(v0[j]); v1[j] = v1[j] * fsigmoid(v1[j]); } }
;                     else if (mode == 3) {
; #pragma unroll
;                         for (int j = 0; j < 4; ++j) { v0[j] = fsigmoid(v0[j]); v1[j] = fsigmoid(v1[j]); } }
;                     u32x4 w; w.x = cvt_pk_bf16(v0[0], v0[1]); w.y = cvt_pk_bf16(v0[2], v0[3]); w.z = cvt_pk_bf16(v1[0], v1[1]); w.w = cvt_pk_bf16(v1[2], v1[3]);
;                     *(u32x4*)(rowp + bj * HALF) = w; } }
	v_add_f32_e32 v22, 1.0, v22
	v_rcp_f32_e32 v24, v23
	v_add_f32_e32 v23, 1.0, v25
	v_add_f32_e32 v25, 1.0, v26
	v_rcp_f32_e32 v18, v18
	v_rcp_f32_e32 v19, v19
	v_rcp_f32_e32 v22, v22
	v_rcp_f32_e32 v23, v23
	v_rcp_f32_e32 v25, v25
	v_rcp_f32_e32 v21, v21
	v_pk_mul_f32 v[18:19], v[14:15], v[18:19]
	v_pk_mul_f32 v[22:23], v[16:17], v[22:23]
	v_pk_mul_f32 v[24:25], v[12:13], v[24:25]
	v_pk_mul_f32 v[20:21], v[10:11], v[20:21]
	v_add_u32_e32 v12, 0xb0, v168
	v_mov_b64_e32 v[10:11], s[92:93]
	v_mad_i64_i32 v[10:11], s[24:25], v12, s80, v[10:11]
	v_lshl_add_u64 v[10:11], v[122:123], 1, v[10:11]
	v_cvt_pk_bf16_f32 v12, v18, v19
	v_cvt_pk_bf16_f32 v13, v22, v23
	v_cvt_pk_bf16_f32 v14, v20, v21
	v_cvt_pk_bf16_f32 v15, v24, v25
	global_store_dwordx4 v[10:11], v[12:15], off
	s_nop 1
	v_mul_f32_e32 v13, 0xbfb8aa3b, v2
	v_mul_f32_e32 v14, 0xbfb8aa3b, v7
	v_exp_f32_e32 v13, v13
	v_exp_f32_e32 v15, v14
	v_mul_f32_e32 v17, 0xbfb8aa3b, v4
	v_mul_f32_e32 v18, 0xbfb8aa3b, v9
	v_add_f32_e32 v13, 1.0, v13
	v_mul_f32_e32 v12, 0xbfb8aa3b, v6
	v_rcp_f32_e32 v14, v13
	v_add_f32_e32 v13, 1.0, v15
	v_mul_f32_e32 v15, 0xbfb8aa3b, v3
	v_mul_f32_e32 v16, 0xbfb8aa3b, v8
	v_exp_f32_e32 v17, v17
	v_exp_f32_e32 v19, v18
	v_mul_f32_e32 v18, 0xbfb8aa3b, v5
	v_exp_f32_e32 v12, v12
	v_exp_f32_e32 v15, v15
	v_exp_f32_e32 v16, v16
	v_exp_f32_e32 v20, v18
	v_add_f32_e32 v17, 1.0, v17
	v_add_f32_e32 v12, 1.0, v12
	v_add_f32_e32 v15, 1.0, v15
	v_add_f32_e32 v16, 1.0, v16
	v_rcp_f32_e32 v18, v17
	v_add_f32_e32 v17, 1.0, v19
	v_add_f32_e32 v19, 1.0, v20
	v_rcp_f32_e32 v12, v12
	v_rcp_f32_e32 v13, v13
	v_rcp_f32_e32 v16, v16
	v_rcp_f32_e32 v17, v17
	v_rcp_f32_e32 v19, v19
	v_rcp_f32_e32 v15, v15
	v_pk_mul_f32 v[12:13], v[6:7], v[12:13]
	v_pk_mul_f32 v[16:17], v[8:9], v[16:17]
	v_pk_mul_f32 v[18:19], v[4:5], v[18:19]
	v_pk_mul_f32 v[14:15], v[2:3], v[14:15]
	v_cvt_pk_bf16_f32 v2, v12, v13
	v_cvt_pk_bf16_f32 v3, v16, v17
	v_cvt_pk_bf16_f32 v4, v14, v15
	v_cvt_pk_bf16_f32 v5, v18, v19
	s_branch .Lepi_tail
.Lepi_class_2:
	s_mov_b32 s82, 0xca30000
	s_mov_b32 s83, 0x10a40000
	v_pk_mul_f32 v[160:161], v[146:147], s[66:67] op_sel_hi:[1,0]
	v_pk_mul_f32 v[156:157], v[144:145], s[66:67] op_sel_hi:[1,0]
	v_pk_mul_f32 v[162:163], v[124:125], s[66:67] op_sel_hi:[1,0]
	v_pk_mul_f32 v[158:159], v[122:123], s[66:67] op_sel_hi:[1,0]
	v_lshl_add_u32 v168, s27, 8, v164
	v_lshl_or_b32 v122, s26, 8, v166
	v_mov_b64_e32 v[124:125], s[92:93]
	v_ashrrev_i32_e32 v123, 31, v122
	v_mad_i64_i32 v[124:125], s[8:9], v168, s80, v[124:125]
	v_lshl_add_u64 v[124:125], v[122:123], 1, v[124:125]
	v_cvt_pk_bf16_f32 v144, v156, v157
	v_cvt_pk_bf16_f32 v145, v160, v161
	v_cvt_pk_bf16_f32 v146, v158, v159
	v_cvt_pk_bf16_f32 v147, v162, v163
	global_store_dwordx4 v[124:125], v[144:147], off
	v_pk_mul_f32 v[156:157], v[120:121], s[66:67] op_sel_hi:[1,0]
	s_nop 0
	v_pk_mul_f32 v[144:145], v[118:119], s[66:67] op_sel_hi:[1,0]
	v_pk_mul_f32 v[158:159], v[116:117], s[66:67] op_sel_hi:[1,0]
	v_pk_mul_f32 v[146:147], v[114:115], s[66:67] op_sel_hi:[1,0]
	v_cvt_pk_bf16_f32 v114, v144, v145
	v_cvt_pk_bf16_f32 v115, v156, v157
	v_cvt_pk_bf16_f32 v116, v146, v147
	v_cvt_pk_bf16_f32 v117, v158, v159
	global_store_dwordx4 v[124:125], v[114:117], off offset:256
	v_pk_mul_f32 v[118:119], v[112:113], s[66:67] op_sel_hi:[1,0]
	s_nop 0
	v_pk_mul_f32 v[114:115], v[110:111], s[66:67] op_sel_hi:[1,0]
	v_pk_mul_f32 v[120:121], v[108:109], s[66:67] op_sel_hi:[1,0]
	v_pk_mul_f32 v[116:117], v[106:107], s[66:67] op_sel_hi:[1,0]
	v_or_b32_e32 v108, 16, v168
	v_mov_b64_e32 v[106:107], s[92:93]
	v_mad_i64_i32 v[106:107], s[24:25], v108, s80, v[106:107]
	v_lshl_add_u64 v[106:107], v[122:123], 1, v[106:107]
	v_cvt_pk_bf16_f32 v108, v114, v115
	v_cvt_pk_bf16_f32 v109, v118, v119
	v_cvt_pk_bf16_f32 v110, v116, v117
	v_cvt_pk_bf16_f32 v111, v120, v121
	global_store_dwordx4 v[106:107], v[108:111], off
	v_pk_mul_f32 v[112:113], v[104:105], s[66:67] op_sel_hi:[1,0]
	s_nop 0
	v_pk_mul_f32 v[108:109], v[102:103], s[66:67] op_sel_hi:[1,0]
	v_pk_mul_f32 v[114:115], v[100:101], s[66:67] op_sel_hi:[1,0]
	v_pk_mul_f32 v[110:111], v[98:99], s[66:67] op_sel_hi:[1,0]
	v_cvt_pk_bf16_f32 v98, v108, v109
	v_cvt_pk_bf16_f32 v99, v112, v113
	v_cvt_pk_bf16_f32 v100, v110, v111
	v_cvt_pk_bf16_f32 v101, v114, v115
	global_store_dwordx4 v[106:107], v[98:101], off offset:256
	v_pk_mul_f32 v[102:103], v[96:97], s[66:67] op_sel_hi:[1,0]
	s_nop 0
	v_pk_mul_f32 v[98:99], v[94:95], s[66:67] op_sel_hi:[1,0]
	v_pk_mul_f32 v[104:105], v[92:93], s[66:67] op_sel_hi:[1,0]
	v_pk_mul_f32 v[100:101], v[90:91], s[66:67] op_sel_hi:[1,0]
	v_or_b32_e32 v92, 32, v168
	v_mov_b64_e32 v[90:91], s[92:93]
	v_mad_i64_i32 v[90:91], s[24:25], v92, s80, v[90:91]
	v_lshl_add_u64 v[90:91], v[122:123], 1, v[90:91]
	v_cvt_pk_bf16_f32 v92, v98, v99
	v_cvt_pk_bf16_f32 v93, v102, v103
	v_cvt_pk_bf16_f32 v94, v100, v101
	v_cvt_pk_bf16_f32 v95, v104, v105
	global_store_dwordx4 v[90:91], v[92:95], off
	v_pk_mul_f32 v[96:97], v[88:89], s[66:67] op_sel_hi:[1,0]
	s_nop 0
	v_pk_mul_f32 v[92:93], v[86:87], s[66:67] op_sel_hi:[1,0]
	v_pk_mul_f32 v[98:99], v[84:85], s[66:67] op_sel_hi:[1,0]
	v_pk_mul_f32 v[94:95], v[82:83], s[66:67] op_sel_hi:[1,0]
	v_cvt_pk_bf16_f32 v82, v92, v93
	v_cvt_pk_bf16_f32 v83, v96, v97
	v_cvt_pk_bf16_f32 v84, v94, v95
	v_cvt_pk_bf16_f32 v85, v98, v99
	global_store_dwordx4 v[90:91], v[82:85], off offset:256
	v_pk_mul_f32 v[86:87], v[80:81], s[66:67] op_sel_hi:[1,0]
	s_nop 0
	v_pk_mul_f32 v[82:83], v[78:79], s[66:67] op_sel_hi:[1,0]
	v_pk_mul_f32 v[88:89], v[76:77], s[66:67] op_sel_hi:[1,0]
	v_pk_mul_f32 v[84:85], v[74:75], s[66:67] op_sel_hi:[1,0]
	v_or_b32_e32 v76, 48, v168
; __device__ __forceinline__ unsigned cvt_pk_bf16(float lo, float hi) { const f32x2e_t v = {lo, hi}; return __builtin_bit_cast(unsigned, __builtin_convertvector(v, bf16x2e_t)); }
; __device__ __forceinline__ float fsigmoid(float v) { return __builtin_amdgcn_rcpf(1.f + __expf(-v)); }
;     __device__ __forceinline__ void operator()(const f32x4 (&acc)[2][2][4][2], const Unit& u, int wr, int wc, int fr, int fq) const {
;     ...
;             for (int m = 0; m < 4; ++m) { bf16_t* rowp = Z + (size_t)(row0 + ai * HALF + m * 16) * ldz + col0;
; #pragma unroll
;                 for (int bj = 0; bj < 2; ++bj) { f32x4 v0 = acc[ai][bj][m][0], v1 = acc[ai][bj][m][1];
;                     if (mode == 1) { v0 = v0 * 0.18033688011112042f; v1 = v1 * 0.18033688011112042f; }
;                     else if (mode == 2) {
; #pragma unroll
;                         for (int j = 0; j < 4; ++j) { v0[j] = v0[j] * fsigmoid(v0[j]); v1[j] = v1[j] * fsigmoid(v1[j]); } }
;                     else if (mode == 3) {
; #pragma unroll
;                         for (int j = 0; j < 4; ++j) { v0[j] = fsigmoid(v0[j]); v1[j] = fsigmoid(v1[j]); } }
;                     u32x4 w; w.x = cvt_pk_bf16(v0[0], v0[1]); w.y = cvt_pk_bf16(v0[2], v0[3]); w.z = cvt_pk_bf16(v1[0], v1[1]); w.w = cvt_pk_bf16(v1[2], v1[3]);
;                     *(u32x4*)(rowp + bj * HALF) = w; } }
	v_mov_b64_e32 v[74:75], s[92:93]
	v_mad_i64_i32 v[74:75], s[24:25], v76, s80, v[74:75]
	v_lshl_add_u64 v[74:75], v[122:123], 1, v[74:75]
	v_cvt_pk_bf16_f32 v76, v82, v83
	v_cvt_pk_bf16_f32 v77, v86, v87
	v_cvt_pk_bf16_f32 v78, v84, v85
	v_cvt_pk_bf16_f32 v79, v88, v89
	global_store_dwordx4 v[74:75], v[76:79], off
	v_pk_mul_f32 v[80:81], v[72:73], s[66:67] op_sel_hi:[1,0]
	s_nop 0
	v_pk_mul_f32 v[76:77], v[70:71], s[66:67] op_sel_hi:[1,0]
	v_pk_mul_f32 v[82:83], v[68:69], s[66:67] op_sel_hi:[1,0]
	v_pk_mul_f32 v[78:79], v[66:67], s[66:67] op_sel_hi:[1,0]
	v_cvt_pk_bf16_f32 v66, v76, v77
	v_cvt_pk_bf16_f32 v67, v80, v81
	v_cvt_pk_bf16_f32 v68, v78, v79
	v_cvt_pk_bf16_f32 v69, v82, v83
	global_store_dwordx4 v[74:75], v[66:69], off offset:256
	v_pk_mul_f32 v[70:71], v[64:65], s[66:67] op_sel_hi:[1,0]
	s_nop 0
	v_pk_mul_f32 v[66:67], v[62:63], s[66:67] op_sel_hi:[1,0]
	v_pk_mul_f32 v[72:73], v[60:61], s[66:67] op_sel_hi:[1,0]
	v_pk_mul_f32 v[68:69], v[58:59], s[66:67] op_sel_hi:[1,0]
	v_add_u32_e32 v60, 0x80, v168
	v_mov_b64_e32 v[58:59], s[92:93]
	v_mad_i64_i32 v[58:59], s[24:25], v60, s80, v[58:59]
	v_lshl_add_u64 v[58:59], v[122:123], 1, v[58:59]
	v_cvt_pk_bf16_f32 v60, v66, v67
	v_cvt_pk_bf16_f32 v61, v70, v71
	v_cvt_pk_bf16_f32 v62, v68, v69
	v_cvt_pk_bf16_f32 v63, v72, v73
	global_store_dwordx4 v[58:59], v[60:63], off
	v_pk_mul_f32 v[64:65], v[56:57], s[66:67] op_sel_hi:[1,0]
	s_nop 0
	v_pk_mul_f32 v[60:61], v[54:55], s[66:67] op_sel_hi:[1,0]
	v_pk_mul_f32 v[66:67], v[52:53], s[66:67] op_sel_hi:[1,0]
	v_pk_mul_f32 v[62:63], v[50:51], s[66:67] op_sel_hi:[1,0]
	v_cvt_pk_bf16_f32 v50, v60, v61
	v_cvt_pk_bf16_f32 v51, v64, v65
	v_cvt_pk_bf16_f32 v52, v62, v63
	v_cvt_pk_bf16_f32 v53, v66, v67
	global_store_dwordx4 v[58:59], v[50:53], off offset:256
	v_pk_mul_f32 v[54:55], v[48:49], s[66:67] op_sel_hi:[1,0]
	s_nop 0
	v_pk_mul_f32 v[50:51], v[46:47], s[66:67] op_sel_hi:[1,0]
	v_pk_mul_f32 v[56:57], v[44:45], s[66:67] op_sel_hi:[1,0]
	v_pk_mul_f32 v[52:53], v[42:43], s[66:67] op_sel_hi:[1,0]
	v_add_u32_e32 v44, 0x90, v168
	v_mov_b64_e32 v[42:43], s[92:93]
	v_mad_i64_i32 v[42:43], s[24:25], v44, s80, v[42:43]
	v_lshl_add_u64 v[42:43], v[122:123], 1, v[42:43]
	v_cvt_pk_bf16_f32 v44, v50, v51
	v_cvt_pk_bf16_f32 v45, v54, v55
	v_cvt_pk_bf16_f32 v46, v52, v53
	v_cvt_pk_bf16_f32 v47, v56, v57
	global_store_dwordx4 v[42:43], v[44:47], off
	v_pk_mul_f32 v[48:49], v[40:41], s[66:67] op_sel_hi:[1,0]
	s_nop 0
	v_pk_mul_f32 v[44:45], v[38:39], s[66:67] op_sel_hi:[1,0]
	v_pk_mul_f32 v[50:51], v[36:37], s[66:67] op_sel_hi:[1,0]
	v_pk_mul_f32 v[46:47], v[34:35], s[66:67] op_sel_hi:[1,0]
	v_cvt_pk_bf16_f32 v34, v44, v45
	v_cvt_pk_bf16_f32 v35, v48, v49
	v_cvt_pk_bf16_f32 v36, v46, v47
	v_cvt_pk_bf16_f32 v37, v50, v51
	global_store_dwordx4 v[42:43], v[34:37], off offset:256
	v_pk_mul_f32 v[38:39], v[32:33], s[66:67] op_sel_hi:[1,0]
	s_nop 0
	v_pk_mul_f32 v[34:35], v[30:31], s[66:67] op_sel_hi:[1,0]
	v_pk_mul_f32 v[40:41], v[28:29], s[66:67] op_sel_hi:[1,0]
	v_pk_mul_f32 v[36:37], v[26:27], s[66:67] op_sel_hi:[1,0]
	v_add_u32_e32 v28, 0xa0, v168
	v_mov_b64_e32 v[26:27], s[92:93]
	v_mad_i64_i32 v[26:27], s[24:25], v28, s80, v[26:27]
	v_lshl_add_u64 v[26:27], v[122:123], 1, v[26:27]
	v_cvt_pk_bf16_f32 v28, v34, v35
	v_cvt_pk_bf16_f32 v29, v38, v39
	v_cvt_pk_bf16_f32 v30, v36, v37
	v_cvt_pk_bf16_f32 v31, v40, v41
	global_store_dwordx4 v[26:27], v[28:31], off
	v_pk_mul_f32 v[32:33], v[24:25], s[66:67] op_sel_hi:[1,0]
	s_nop 0
	v_pk_mul_f32 v[28:29], v[22:23], s[66:67] op_sel_hi:[1,0]
	v_pk_mul_f32 v[34:35], v[20:21], s[66:67] op_sel_hi:[1,0]
	v_pk_mul_f32 v[30:31], v[18:19], s[66:67] op_sel_hi:[1,0]
	v_cvt_pk_bf16_f32 v18, v28, v29
	v_cvt_pk_bf16_f32 v19, v32, v33
	v_cvt_pk_bf16_f32 v20, v30, v31
	v_cvt_pk_bf16_f32 v21, v34, v35
	global_store_dwordx4 v[26:27], v[18:21], off offset:256
	v_pk_mul_f32 v[22:23], v[16:17], s[66:67] op_sel_hi:[1,0]
	s_nop 0
	v_pk_mul_f32 v[18:19], v[14:15], s[66:67] op_sel_hi:[1,0]
	v_pk_mul_f32 v[24:25], v[12:13], s[66:67] op_sel_hi:[1,0]
	v_pk_mul_f32 v[20:21], v[10:11], s[66:67] op_sel_hi:[1,0]
	v_add_u32_e32 v12, 0xb0, v168
	v_mov_b64_e32 v[10:11], s[92:93]
	v_mad_i64_i32 v[10:11], s[24:25], v12, s80, v[10:11]
	v_lshl_add_u64 v[10:11], v[122:123], 1, v[10:11]
	v_cvt_pk_bf16_f32 v12, v18, v19
	v_cvt_pk_bf16_f32 v13, v22, v23
	v_cvt_pk_bf16_f32 v14, v20, v21
	v_cvt_pk_bf16_f32 v15, v24, v25
	global_store_dwordx4 v[10:11], v[12:15], off
	v_pk_mul_f32 v[16:17], v[8:9], s[66:67] op_sel_hi:[1,0]
	s_nop 0
	v_pk_mul_f32 v[12:13], v[6:7], s[66:67] op_sel_hi:[1,0]
	v_pk_mul_f32 v[18:19], v[4:5], s[66:67] op_sel_hi:[1,0]
	v_pk_mul_f32 v[14:15], v[2:3], s[66:67] op_sel_hi:[1,0]
	v_cvt_pk_bf16_f32 v2, v12, v13
	v_cvt_pk_bf16_f32 v3, v16, v17
	v_cvt_pk_bf16_f32 v4, v14, v15
	v_cvt_pk_bf16_f32 v5, v18, v19
	s_branch .Lepi_tail
; __device__ __forceinline__ unsigned cvt_pk_bf16(float lo, float hi) { const f32x2e_t v = {lo, hi}; return __builtin_bit_cast(unsigned, __builtin_convertvector(v, bf16x2e_t)); }
; __device__ __forceinline__ float fsigmoid(float v) { return __builtin_amdgcn_rcpf(1.f + __expf(-v)); }
;     __device__ __forceinline__ void operator()(const f32x4 (&acc)[2][2][4][2], const Unit& u, int wr, int wc, int fr, int fq) const {
;     ...
;             for (int m = 0; m < 4; ++m) { bf16_t* rowp = Z + (size_t)(row0 + ai * HALF + m * 16) * ldz + col0;
; #pragma unroll
;                 for (int bj = 0; bj < 2; ++bj) { f32x4 v0 = acc[ai][bj][m][0], v1 = acc[ai][bj][m][1];
;                     if (mode == 1) { v0 = v0 * 0.18033688011112042f; v1 = v1 * 0.18033688011112042f; }
;                     else if (mode == 2) {
; #pragma unroll
;                         for (int j = 0; j < 4; ++j) { v0[j] = v0[j] * fsigmoid(v0[j]); v1[j] = v1[j] * fsigmoid(v1[j]); } }
;                     else if (mode == 3) {
; #pragma unroll
;                         for (int j = 0; j < 4; ++j) { v0[j] = fsigmoid(v0[j]); v1[j] = fsigmoid(v1[j]); } }
;                     u32x4 w; w.x = cvt_pk_bf16(v0[0], v0[1]); w.y = cvt_pk_bf16(v0[2], v0[3]); w.z = cvt_pk_bf16(v1[0], v1[1]); w.w = cvt_pk_bf16(v1[2], v1[3]);
;                     *(u32x4*)(rowp + bj * HALF) = w; } }
.Lepi_class_3:
	s_mov_b32 s82, 0xca30000
	s_mov_b32 s83, 0x10a40000
	v_mov_b32_e32 v163, v125
	v_mov_b32_e32 v162, v124
	v_mov_b32_e32 v159, v123
	v_mov_b32_e32 v158, v122
	v_mov_b32_e32 v161, v147
	v_mov_b32_e32 v160, v146
	v_mov_b32_e32 v157, v145
	v_mov_b32_e32 v156, v144
	v_mul_f32_e32 v157, 0xbfb8aa3b, v122
	v_mul_f32_e32 v158, 0xbfb8aa3b, v145
	v_exp_f32_e32 v157, v157
	v_exp_f32_e32 v159, v158
	v_mul_f32_e32 v158, 0xbfb8aa3b, v123
	v_exp_f32_e32 v160, v158
	v_add_f32_e32 v157, 1.0, v157
	v_mul_f32_e32 v161, 0xbfb8aa3b, v124
	v_mul_f32_e32 v162, 0xbfb8aa3b, v147
	v_mul_f32_e32 v156, 0xbfb8aa3b, v144
	v_rcp_f32_e32 v158, v157
	v_add_f32_e32 v157, 1.0, v159
	v_add_f32_e32 v159, 1.0, v160
	v_mul_f32_e32 v160, 0xbfb8aa3b, v146
	v_exp_f32_e32 v161, v161
	v_exp_f32_e32 v163, v162
	v_mul_f32_e32 v162, 0xbfb8aa3b, v125
	v_exp_f32_e32 v156, v156
	v_exp_f32_e32 v160, v160
	v_exp_f32_e32 v168, v162
	v_add_f32_e32 v161, 1.0, v161
	v_add_f32_e32 v156, 1.0, v156
	v_add_f32_e32 v160, 1.0, v160
	v_rcp_f32_e32 v162, v161
	v_add_f32_e32 v161, 1.0, v163
	v_add_f32_e32 v163, 1.0, v168
	v_rcp_f32_e32 v156, v156
	v_rcp_f32_e32 v157, v157
	v_rcp_f32_e32 v159, v159
	v_rcp_f32_e32 v160, v160
	v_rcp_f32_e32 v161, v161
	v_rcp_f32_e32 v163, v163
	v_lshl_add_u32 v168, s27, 8, v164
	v_lshl_or_b32 v122, s26, 8, v166
	v_mov_b64_e32 v[124:125], s[92:93]
	v_ashrrev_i32_e32 v123, 31, v122
	v_mad_i64_i32 v[124:125], s[8:9], v168, s80, v[124:125]
	v_lshl_add_u64 v[124:125], v[122:123], 1, v[124:125]
	v_cvt_pk_bf16_f32 v144, v156, v157
	v_cvt_pk_bf16_f32 v145, v160, v161
	v_cvt_pk_bf16_f32 v146, v158, v159
	v_cvt_pk_bf16_f32 v147, v162, v163
	global_store_dwordx4 v[124:125], v[144:147], off
	v_mov_b32_e32 v159, v117
	v_mov_b32_e32 v158, v116
	v_mov_b32_e32 v147, v115
	v_mov_b32_e32 v146, v114
	v_mov_b32_e32 v157, v121
	v_mov_b32_e32 v156, v120
	v_mov_b32_e32 v145, v119
	v_mov_b32_e32 v144, v118
	v_mul_f32_e32 v145, 0xbfb8aa3b, v114
	v_mul_f32_e32 v146, 0xbfb8aa3b, v119
	v_exp_f32_e32 v145, v145
	v_exp_f32_e32 v147, v146
	v_mul_f32_e32 v146, 0xbfb8aa3b, v115
	v_exp_f32_e32 v156, v146
	v_add_f32_e32 v145, 1.0, v145
	v_mul_f32_e32 v157, 0xbfb8aa3b, v116
	v_mul_f32_e32 v158, 0xbfb8aa3b, v121
	v_mul_f32_e32 v144, 0xbfb8aa3b, v118
	v_rcp_f32_e32 v146, v145
	v_add_f32_e32 v145, 1.0, v147
	v_add_f32_e32 v147, 1.0, v156
	v_mul_f32_e32 v156, 0xbfb8aa3b, v120
	v_exp_f32_e32 v157, v157
	v_exp_f32_e32 v159, v158
	v_mul_f32_e32 v158, 0xbfb8aa3b, v117
	v_exp_f32_e32 v144, v144
	v_exp_f32_e32 v156, v156
	v_exp_f32_e32 v160, v158
	v_add_f32_e32 v157, 1.0, v157
	v_add_f32_e32 v144, 1.0, v144
	v_add_f32_e32 v156, 1.0, v156
	v_rcp_f32_e32 v158, v157
	v_add_f32_e32 v157, 1.0, v159
	v_add_f32_e32 v159, 1.0, v160
	v_rcp_f32_e32 v144, v144
	v_rcp_f32_e32 v145, v145
	v_rcp_f32_e32 v147, v147
	v_rcp_f32_e32 v156, v156
	v_rcp_f32_e32 v157, v157
	v_rcp_f32_e32 v159, v159
	v_cvt_pk_bf16_f32 v114, v144, v145
	v_cvt_pk_bf16_f32 v115, v156, v157
	v_cvt_pk_bf16_f32 v116, v146, v147
	v_cvt_pk_bf16_f32 v117, v158, v159
	global_store_dwordx4 v[124:125], v[114:117], off offset:256
	v_mov_b32_e32 v121, v109
	v_mov_b32_e32 v120, v108
	v_mov_b32_e32 v117, v107
	v_mov_b32_e32 v116, v106
	v_mov_b32_e32 v119, v113
	v_mov_b32_e32 v118, v112
	v_mov_b32_e32 v115, v111
	v_mov_b32_e32 v114, v110
	v_mul_f32_e32 v115, 0xbfb8aa3b, v106
	v_mul_f32_e32 v116, 0xbfb8aa3b, v111
	v_exp_f32_e32 v115, v115
	v_exp_f32_e32 v117, v116
	v_mul_f32_e32 v116, 0xbfb8aa3b, v107
	v_exp_f32_e32 v118, v116
	v_add_f32_e32 v115, 1.0, v115
	v_mul_f32_e32 v119, 0xbfb8aa3b, v108
	v_mul_f32_e32 v120, 0xbfb8aa3b, v113
	v_mul_f32_e32 v114, 0xbfb8aa3b, v110
	v_rcp_f32_e32 v116, v115
	v_add_f32_e32 v115, 1.0, v117
	v_add_f32_e32 v117, 1.0, v118
	v_mul_f32_e32 v118, 0xbfb8aa3b, v112
	v_exp_f32_e32 v119, v119
	v_exp_f32_e32 v121, v120
	v_mul_f32_e32 v120, 0xbfb8aa3b, v109
	v_exp_f32_e32 v114, v114
	v_exp_f32_e32 v118, v118
	v_exp_f32_e32 v124, v120
	v_add_f32_e32 v119, 1.0, v119
	v_add_f32_e32 v114, 1.0, v114
	v_add_f32_e32 v118, 1.0, v118
	v_rcp_f32_e32 v120, v119
	v_add_f32_e32 v119, 1.0, v121
	v_add_f32_e32 v121, 1.0, v124
	v_rcp_f32_e32 v114, v114
	v_rcp_f32_e32 v115, v115
	v_rcp_f32_e32 v117, v117
	v_rcp_f32_e32 v118, v118
	v_rcp_f32_e32 v119, v119
	v_rcp_f32_e32 v121, v121
	v_or_b32_e32 v108, 16, v168
	v_mov_b64_e32 v[106:107], s[92:93]
	v_mad_i64_i32 v[106:107], s[24:25], v108, s80, v[106:107]
	v_lshl_add_u64 v[106:107], v[122:123], 1, v[106:107]
	v_cvt_pk_bf16_f32 v108, v114, v115
	v_cvt_pk_bf16_f32 v109, v118, v119
	v_cvt_pk_bf16_f32 v110, v116, v117
	v_cvt_pk_bf16_f32 v111, v120, v121
	global_store_dwordx4 v[106:107], v[108:111], off
	v_mov_b32_e32 v115, v101
	v_mov_b32_e32 v114, v100
	v_mov_b32_e32 v111, v99
	v_mov_b32_e32 v110, v98
	v_mov_b32_e32 v113, v105
	v_mov_b32_e32 v112, v104
	v_mov_b32_e32 v109, v103
	v_mov_b32_e32 v108, v102
	v_mul_f32_e32 v109, 0xbfb8aa3b, v98
	v_mul_f32_e32 v110, 0xbfb8aa3b, v103
	v_exp_f32_e32 v109, v109
	v_exp_f32_e32 v111, v110
	v_mul_f32_e32 v110, 0xbfb8aa3b, v99
	v_exp_f32_e32 v112, v110
	v_add_f32_e32 v109, 1.0, v109
	v_mul_f32_e32 v113, 0xbfb8aa3b, v100
	v_mul_f32_e32 v114, 0xbfb8aa3b, v105
	v_mul_f32_e32 v108, 0xbfb8aa3b, v102
	v_rcp_f32_e32 v110, v109
	v_add_f32_e32 v109, 1.0, v111
	v_add_f32_e32 v111, 1.0, v112
	v_mul_f32_e32 v112, 0xbfb8aa3b, v104
	v_exp_f32_e32 v113, v113
	v_exp_f32_e32 v115, v114
	v_mul_f32_e32 v114, 0xbfb8aa3b, v101
	v_exp_f32_e32 v108, v108
	v_exp_f32_e32 v112, v112
	v_exp_f32_e32 v116, v114
	v_add_f32_e32 v113, 1.0, v113
	v_add_f32_e32 v108, 1.0, v108
	v_add_f32_e32 v112, 1.0, v112
	v_rcp_f32_e32 v114, v113
	v_add_f32_e32 v113, 1.0, v115
	v_add_f32_e32 v115, 1.0, v116
; __device__ __forceinline__ unsigned cvt_pk_bf16(float lo, float hi) { const f32x2e_t v = {lo, hi}; return __builtin_bit_cast(unsigned, __builtin_convertvector(v, bf16x2e_t)); }
; __device__ __forceinline__ float fsigmoid(float v) { return __builtin_amdgcn_rcpf(1.f + __expf(-v)); }
;     __device__ __forceinline__ void operator()(const f32x4 (&acc)[2][2][4][2], const Unit& u, int wr, int wc, int fr, int fq) const {
;     ...
;             for (int m = 0; m < 4; ++m) { bf16_t* rowp = Z + (size_t)(row0 + ai * HALF + m * 16) * ldz + col0;
; #pragma unroll
;                 for (int bj = 0; bj < 2; ++bj) { f32x4 v0 = acc[ai][bj][m][0], v1 = acc[ai][bj][m][1];
;                     if (mode == 1) { v0 = v0 * 0.18033688011112042f; v1 = v1 * 0.18033688011112042f; }
;                     else if (mode == 2) {
; #pragma unroll
;                         for (int j = 0; j < 4; ++j) { v0[j] = v0[j] * fsigmoid(v0[j]); v1[j] = v1[j] * fsigmoid(v1[j]); } }
;                     else if (mode == 3) {
; #pragma unroll
;                         for (int j = 0; j < 4; ++j) { v0[j] = fsigmoid(v0[j]); v1[j] = fsigmoid(v1[j]); } }
;                     u32x4 w; w.x = cvt_pk_bf16(v0[0], v0[1]); w.y = cvt_pk_bf16(v0[2], v0[3]); w.z = cvt_pk_bf16(v1[0], v1[1]); w.w = cvt_pk_bf16(v1[2], v1[3]);
;                     *(u32x4*)(rowp + bj * HALF) = w; } }
	v_rcp_f32_e32 v108, v108
	v_rcp_f32_e32 v109, v109
	v_rcp_f32_e32 v111, v111
	v_rcp_f32_e32 v112, v112
	v_rcp_f32_e32 v113, v113
	v_rcp_f32_e32 v115, v115
	v_cvt_pk_bf16_f32 v98, v108, v109
	v_cvt_pk_bf16_f32 v99, v112, v113
	v_cvt_pk_bf16_f32 v100, v110, v111
	v_cvt_pk_bf16_f32 v101, v114, v115
	global_store_dwordx4 v[106:107], v[98:101], off offset:256
	v_mov_b32_e32 v105, v93
	v_mov_b32_e32 v104, v92
	v_mov_b32_e32 v101, v91
	v_mov_b32_e32 v100, v90
	v_mov_b32_e32 v103, v97
	v_mov_b32_e32 v102, v96
	v_mov_b32_e32 v99, v95
	v_mov_b32_e32 v98, v94
	v_mul_f32_e32 v99, 0xbfb8aa3b, v90
	v_mul_f32_e32 v100, 0xbfb8aa3b, v95
	v_exp_f32_e32 v99, v99
	v_exp_f32_e32 v101, v100
	v_mul_f32_e32 v100, 0xbfb8aa3b, v91
	v_exp_f32_e32 v102, v100
	v_add_f32_e32 v99, 1.0, v99
	v_mul_f32_e32 v103, 0xbfb8aa3b, v92
	v_mul_f32_e32 v104, 0xbfb8aa3b, v97
	v_mul_f32_e32 v98, 0xbfb8aa3b, v94
	v_rcp_f32_e32 v100, v99
	v_add_f32_e32 v99, 1.0, v101
	v_add_f32_e32 v101, 1.0, v102
	v_mul_f32_e32 v102, 0xbfb8aa3b, v96
	v_exp_f32_e32 v103, v103
	v_exp_f32_e32 v105, v104
	v_mul_f32_e32 v104, 0xbfb8aa3b, v93
	v_exp_f32_e32 v98, v98
	v_exp_f32_e32 v102, v102
	v_exp_f32_e32 v106, v104
	v_add_f32_e32 v103, 1.0, v103
	v_add_f32_e32 v98, 1.0, v98
	v_add_f32_e32 v102, 1.0, v102
	v_rcp_f32_e32 v104, v103
	v_add_f32_e32 v103, 1.0, v105
	v_add_f32_e32 v105, 1.0, v106
	v_rcp_f32_e32 v98, v98
	v_rcp_f32_e32 v99, v99
	v_rcp_f32_e32 v101, v101
	v_rcp_f32_e32 v102, v102
	v_rcp_f32_e32 v103, v103
	v_rcp_f32_e32 v105, v105
	v_or_b32_e32 v92, 32, v168
	v_mov_b64_e32 v[90:91], s[92:93]
	v_mad_i64_i32 v[90:91], s[24:25], v92, s80, v[90:91]
	v_lshl_add_u64 v[90:91], v[122:123], 1, v[90:91]
	v_cvt_pk_bf16_f32 v92, v98, v99
	v_cvt_pk_bf16_f32 v93, v102, v103
	v_cvt_pk_bf16_f32 v94, v100, v101
	v_cvt_pk_bf16_f32 v95, v104, v105
	global_store_dwordx4 v[90:91], v[92:95], off
	v_mov_b32_e32 v99, v85
	v_mov_b32_e32 v98, v84
	v_mov_b32_e32 v95, v83
	v_mov_b32_e32 v94, v82
	v_mov_b32_e32 v97, v89
	v_mov_b32_e32 v96, v88
	v_mov_b32_e32 v93, v87
	v_mov_b32_e32 v92, v86
	v_mul_f32_e32 v93, 0xbfb8aa3b, v82
	v_mul_f32_e32 v94, 0xbfb8aa3b, v87
	v_exp_f32_e32 v93, v93
	v_exp_f32_e32 v95, v94
	v_mul_f32_e32 v94, 0xbfb8aa3b, v83
	v_exp_f32_e32 v96, v94
	v_add_f32_e32 v93, 1.0, v93
	v_mul_f32_e32 v97, 0xbfb8aa3b, v84
	v_mul_f32_e32 v98, 0xbfb8aa3b, v89
	v_mul_f32_e32 v92, 0xbfb8aa3b, v86
	v_rcp_f32_e32 v94, v93
	v_add_f32_e32 v93, 1.0, v95
	v_add_f32_e32 v95, 1.0, v96
	v_mul_f32_e32 v96, 0xbfb8aa3b, v88
	v_exp_f32_e32 v97, v97
	v_exp_f32_e32 v99, v98
	v_mul_f32_e32 v98, 0xbfb8aa3b, v85
	v_exp_f32_e32 v92, v92
	v_exp_f32_e32 v96, v96
	v_exp_f32_e32 v100, v98
	v_add_f32_e32 v97, 1.0, v97
	v_add_f32_e32 v92, 1.0, v92
	v_add_f32_e32 v96, 1.0, v96
	v_rcp_f32_e32 v98, v97
	v_add_f32_e32 v97, 1.0, v99
	v_add_f32_e32 v99, 1.0, v100
	v_rcp_f32_e32 v92, v92
	v_rcp_f32_e32 v93, v93
	v_rcp_f32_e32 v95, v95
	v_rcp_f32_e32 v96, v96
	v_rcp_f32_e32 v97, v97
	v_rcp_f32_e32 v99, v99
	v_cvt_pk_bf16_f32 v82, v92, v93
	v_cvt_pk_bf16_f32 v83, v96, v97
	v_cvt_pk_bf16_f32 v84, v94, v95
	v_cvt_pk_bf16_f32 v85, v98, v99
	global_store_dwordx4 v[90:91], v[82:85], off offset:256
	v_mov_b32_e32 v89, v77
	v_mov_b32_e32 v88, v76
	v_mov_b32_e32 v85, v75
	v_mov_b32_e32 v84, v74
	v_mov_b32_e32 v87, v81
	v_mov_b32_e32 v86, v80
	v_mov_b32_e32 v83, v79
	v_mov_b32_e32 v82, v78
	v_mul_f32_e32 v83, 0xbfb8aa3b, v74
	v_mul_f32_e32 v84, 0xbfb8aa3b, v79
	v_exp_f32_e32 v83, v83
	v_exp_f32_e32 v85, v84
	v_mul_f32_e32 v84, 0xbfb8aa3b, v75
	v_exp_f32_e32 v86, v84
	v_add_f32_e32 v83, 1.0, v83
	v_mul_f32_e32 v87, 0xbfb8aa3b, v76
	v_mul_f32_e32 v88, 0xbfb8aa3b, v81
	v_mul_f32_e32 v82, 0xbfb8aa3b, v78
	v_rcp_f32_e32 v84, v83
	v_add_f32_e32 v83, 1.0, v85
	v_add_f32_e32 v85, 1.0, v86
	v_mul_f32_e32 v86, 0xbfb8aa3b, v80
	v_exp_f32_e32 v87, v87
	v_exp_f32_e32 v89, v88
	v_mul_f32_e32 v88, 0xbfb8aa3b, v77
	v_exp_f32_e32 v82, v82
	v_exp_f32_e32 v86, v86
	v_exp_f32_e32 v90, v88
	v_add_f32_e32 v87, 1.0, v87
	v_add_f32_e32 v82, 1.0, v82
	v_add_f32_e32 v86, 1.0, v86
	v_rcp_f32_e32 v88, v87
	v_add_f32_e32 v87, 1.0, v89
	v_add_f32_e32 v89, 1.0, v90
	v_rcp_f32_e32 v82, v82
	v_rcp_f32_e32 v83, v83
	v_rcp_f32_e32 v85, v85
	v_rcp_f32_e32 v86, v86
	v_rcp_f32_e32 v87, v87
	v_rcp_f32_e32 v89, v89
	v_or_b32_e32 v76, 48, v168
	v_mov_b64_e32 v[74:75], s[92:93]
	v_mad_i64_i32 v[74:75], s[24:25], v76, s80, v[74:75]
	v_lshl_add_u64 v[74:75], v[122:123], 1, v[74:75]
	v_cvt_pk_bf16_f32 v76, v82, v83
	v_cvt_pk_bf16_f32 v77, v86, v87
	v_cvt_pk_bf16_f32 v78, v84, v85
	v_cvt_pk_bf16_f32 v79, v88, v89
	global_store_dwordx4 v[74:75], v[76:79], off
	v_mov_b32_e32 v83, v69
	v_mov_b32_e32 v82, v68
	v_mov_b32_e32 v79, v67
	v_mov_b32_e32 v78, v66
	v_mov_b32_e32 v81, v73
	v_mov_b32_e32 v80, v72
	v_mov_b32_e32 v77, v71
	v_mov_b32_e32 v76, v70
	v_mul_f32_e32 v77, 0xbfb8aa3b, v66
	v_mul_f32_e32 v78, 0xbfb8aa3b, v71
	v_exp_f32_e32 v77, v77
	v_exp_f32_e32 v79, v78
	v_mul_f32_e32 v78, 0xbfb8aa3b, v67
	v_exp_f32_e32 v80, v78
	v_add_f32_e32 v77, 1.0, v77
	v_mul_f32_e32 v81, 0xbfb8aa3b, v68
	v_mul_f32_e32 v82, 0xbfb8aa3b, v73
	v_mul_f32_e32 v76, 0xbfb8aa3b, v70
	v_rcp_f32_e32 v78, v77
	v_add_f32_e32 v77, 1.0, v79
	v_add_f32_e32 v79, 1.0, v80
	v_mul_f32_e32 v80, 0xbfb8aa3b, v72
	v_exp_f32_e32 v81, v81
	v_exp_f32_e32 v83, v82
	v_mul_f32_e32 v82, 0xbfb8aa3b, v69
	v_exp_f32_e32 v76, v76
	v_exp_f32_e32 v80, v80
	v_exp_f32_e32 v84, v82
	v_add_f32_e32 v81, 1.0, v81
	v_add_f32_e32 v76, 1.0, v76
	v_add_f32_e32 v80, 1.0, v80
	v_rcp_f32_e32 v82, v81
	v_add_f32_e32 v81, 1.0, v83
	v_add_f32_e32 v83, 1.0, v84
	v_rcp_f32_e32 v76, v76
	v_rcp_f32_e32 v77, v77
	v_rcp_f32_e32 v79, v79
	v_rcp_f32_e32 v80, v80
	v_rcp_f32_e32 v81, v81
; __device__ __forceinline__ unsigned cvt_pk_bf16(float lo, float hi) { const f32x2e_t v = {lo, hi}; return __builtin_bit_cast(unsigned, __builtin_convertvector(v, bf16x2e_t)); }
; __device__ __forceinline__ float fsigmoid(float v) { return __builtin_amdgcn_rcpf(1.f + __expf(-v)); }
;     __device__ __forceinline__ void operator()(const f32x4 (&acc)[2][2][4][2], const Unit& u, int wr, int wc, int fr, int fq) const {
;     ...
;             for (int m = 0; m < 4; ++m) { bf16_t* rowp = Z + (size_t)(row0 + ai * HALF + m * 16) * ldz + col0;
; #pragma unroll
;                 for (int bj = 0; bj < 2; ++bj) { f32x4 v0 = acc[ai][bj][m][0], v1 = acc[ai][bj][m][1];
;                     if (mode == 1) { v0 = v0 * 0.18033688011112042f; v1 = v1 * 0.18033688011112042f; }
;                     else if (mode == 2) {
; #pragma unroll
;                         for (int j = 0; j < 4; ++j) { v0[j] = v0[j] * fsigmoid(v0[j]); v1[j] = v1[j] * fsigmoid(v1[j]); } }
;                     else if (mode == 3) {
; #pragma unroll
;                         for (int j = 0; j < 4; ++j) { v0[j] = fsigmoid(v0[j]); v1[j] = fsigmoid(v1[j]); } }
;                     u32x4 w; w.x = cvt_pk_bf16(v0[0], v0[1]); w.y = cvt_pk_bf16(v0[2], v0[3]); w.z = cvt_pk_bf16(v1[0], v1[1]); w.w = cvt_pk_bf16(v1[2], v1[3]);
;                     *(u32x4*)(rowp + bj * HALF) = w; } }
	v_rcp_f32_e32 v83, v83
	v_cvt_pk_bf16_f32 v66, v76, v77
	v_cvt_pk_bf16_f32 v67, v80, v81
	v_cvt_pk_bf16_f32 v68, v78, v79
	v_cvt_pk_bf16_f32 v69, v82, v83
	global_store_dwordx4 v[74:75], v[66:69], off offset:256
	v_mov_b32_e32 v73, v61
	v_mov_b32_e32 v72, v60
	v_mov_b32_e32 v69, v59
	v_mov_b32_e32 v68, v58
	v_mov_b32_e32 v71, v65
	v_mov_b32_e32 v70, v64
	v_mov_b32_e32 v67, v63
	v_mov_b32_e32 v66, v62
	v_mul_f32_e32 v67, 0xbfb8aa3b, v58
	v_mul_f32_e32 v68, 0xbfb8aa3b, v63
	v_exp_f32_e32 v67, v67
	v_exp_f32_e32 v69, v68
	v_mul_f32_e32 v68, 0xbfb8aa3b, v59
	v_exp_f32_e32 v70, v68
	v_add_f32_e32 v67, 1.0, v67
	v_mul_f32_e32 v71, 0xbfb8aa3b, v60
	v_mul_f32_e32 v72, 0xbfb8aa3b, v65
	v_mul_f32_e32 v66, 0xbfb8aa3b, v62
	v_rcp_f32_e32 v68, v67
	v_add_f32_e32 v67, 1.0, v69
	v_add_f32_e32 v69, 1.0, v70
	v_mul_f32_e32 v70, 0xbfb8aa3b, v64
	v_exp_f32_e32 v71, v71
	v_exp_f32_e32 v73, v72
	v_mul_f32_e32 v72, 0xbfb8aa3b, v61
	v_exp_f32_e32 v66, v66
	v_exp_f32_e32 v70, v70
	v_exp_f32_e32 v74, v72
	v_add_f32_e32 v71, 1.0, v71
	v_add_f32_e32 v66, 1.0, v66
	v_add_f32_e32 v70, 1.0, v70
	v_rcp_f32_e32 v72, v71
	v_add_f32_e32 v71, 1.0, v73
	v_add_f32_e32 v73, 1.0, v74
	v_rcp_f32_e32 v66, v66
	v_rcp_f32_e32 v67, v67
	v_rcp_f32_e32 v69, v69
	v_rcp_f32_e32 v70, v70
	v_rcp_f32_e32 v71, v71
	v_rcp_f32_e32 v73, v73
	v_add_u32_e32 v60, 0x80, v168
	v_mov_b64_e32 v[58:59], s[92:93]
	v_mad_i64_i32 v[58:59], s[24:25], v60, s80, v[58:59]
	v_lshl_add_u64 v[58:59], v[122:123], 1, v[58:59]
	v_cvt_pk_bf16_f32 v60, v66, v67
	v_cvt_pk_bf16_f32 v61, v70, v71
	v_cvt_pk_bf16_f32 v62, v68, v69
	v_cvt_pk_bf16_f32 v63, v72, v73
	global_store_dwordx4 v[58:59], v[60:63], off
	v_mov_b32_e32 v67, v53
	v_mov_b32_e32 v66, v52
	v_mov_b32_e32 v63, v51
	v_mov_b32_e32 v62, v50
	v_mov_b32_e32 v65, v57
	v_mov_b32_e32 v64, v56
	v_mov_b32_e32 v61, v55
	v_mov_b32_e32 v60, v54
	v_mul_f32_e32 v61, 0xbfb8aa3b, v50
	v_mul_f32_e32 v62, 0xbfb8aa3b, v55
	v_exp_f32_e32 v61, v61
	v_exp_f32_e32 v63, v62
	v_mul_f32_e32 v62, 0xbfb8aa3b, v51
	v_exp_f32_e32 v64, v62
	v_add_f32_e32 v61, 1.0, v61
	v_mul_f32_e32 v65, 0xbfb8aa3b, v52
	v_mul_f32_e32 v66, 0xbfb8aa3b, v57
	v_mul_f32_e32 v60, 0xbfb8aa3b, v54
	v_rcp_f32_e32 v62, v61
	v_add_f32_e32 v61, 1.0, v63
	v_add_f32_e32 v63, 1.0, v64
	v_mul_f32_e32 v64, 0xbfb8aa3b, v56
	v_exp_f32_e32 v65, v65
	v_exp_f32_e32 v67, v66
	v_mul_f32_e32 v66, 0xbfb8aa3b, v53
	v_exp_f32_e32 v60, v60
	v_exp_f32_e32 v64, v64
	v_exp_f32_e32 v68, v66
	v_add_f32_e32 v65, 1.0, v65
	v_add_f32_e32 v60, 1.0, v60
	v_add_f32_e32 v64, 1.0, v64
	v_rcp_f32_e32 v66, v65
	v_add_f32_e32 v65, 1.0, v67
	v_add_f32_e32 v67, 1.0, v68
	v_rcp_f32_e32 v60, v60
	v_rcp_f32_e32 v61, v61
	v_rcp_f32_e32 v63, v63
	v_rcp_f32_e32 v64, v64
	v_rcp_f32_e32 v65, v65
	v_rcp_f32_e32 v67, v67
	v_cvt_pk_bf16_f32 v50, v60, v61
	v_cvt_pk_bf16_f32 v51, v64, v65
	v_cvt_pk_bf16_f32 v52, v62, v63
	v_cvt_pk_bf16_f32 v53, v66, v67
	global_store_dwordx4 v[58:59], v[50:53], off offset:256
	v_mov_b32_e32 v57, v45
	v_mov_b32_e32 v56, v44
	v_mov_b32_e32 v53, v43
	v_mov_b32_e32 v52, v42
	v_mov_b32_e32 v55, v49
	v_mov_b32_e32 v54, v48
	v_mov_b32_e32 v51, v47
	v_mov_b32_e32 v50, v46
	v_mul_f32_e32 v51, 0xbfb8aa3b, v42
	v_mul_f32_e32 v52, 0xbfb8aa3b, v47
	v_exp_f32_e32 v51, v51
	v_exp_f32_e32 v53, v52
	v_mul_f32_e32 v52, 0xbfb8aa3b, v43
	v_exp_f32_e32 v54, v52
	v_add_f32_e32 v51, 1.0, v51
	v_mul_f32_e32 v55, 0xbfb8aa3b, v44
	v_mul_f32_e32 v56, 0xbfb8aa3b, v49
	v_mul_f32_e32 v50, 0xbfb8aa3b, v46
	v_rcp_f32_e32 v52, v51
	v_add_f32_e32 v51, 1.0, v53
	v_add_f32_e32 v53, 1.0, v54
	v_mul_f32_e32 v54, 0xbfb8aa3b, v48
	v_exp_f32_e32 v55, v55
	v_exp_f32_e32 v57, v56
	v_mul_f32_e32 v56, 0xbfb8aa3b, v45
	v_exp_f32_e32 v50, v50
	v_exp_f32_e32 v54, v54
	v_exp_f32_e32 v58, v56
	v_add_f32_e32 v55, 1.0, v55
	v_add_f32_e32 v50, 1.0, v50
	v_add_f32_e32 v54, 1.0, v54
	v_rcp_f32_e32 v56, v55
	v_add_f32_e32 v55, 1.0, v57
	v_add_f32_e32 v57, 1.0, v58
	v_rcp_f32_e32 v50, v50
	v_rcp_f32_e32 v51, v51
	v_rcp_f32_e32 v53, v53
	v_rcp_f32_e32 v54, v54
	v_rcp_f32_e32 v55, v55
	v_rcp_f32_e32 v57, v57
	v_add_u32_e32 v44, 0x90, v168
	v_mov_b64_e32 v[42:43], s[92:93]
	v_mad_i64_i32 v[42:43], s[24:25], v44, s80, v[42:43]
	v_lshl_add_u64 v[42:43], v[122:123], 1, v[42:43]
	v_cvt_pk_bf16_f32 v44, v50, v51
	v_cvt_pk_bf16_f32 v45, v54, v55
	v_cvt_pk_bf16_f32 v46, v52, v53
	v_cvt_pk_bf16_f32 v47, v56, v57
	global_store_dwordx4 v[42:43], v[44:47], off
	v_mov_b32_e32 v51, v37
	v_mov_b32_e32 v50, v36
	v_mov_b32_e32 v47, v35
	v_mov_b32_e32 v46, v34
	v_mov_b32_e32 v49, v41
	v_mov_b32_e32 v48, v40
	v_mov_b32_e32 v45, v39
	v_mov_b32_e32 v44, v38
	v_mul_f32_e32 v45, 0xbfb8aa3b, v34
	v_mul_f32_e32 v46, 0xbfb8aa3b, v39
	v_exp_f32_e32 v45, v45
	v_exp_f32_e32 v47, v46
	v_mul_f32_e32 v46, 0xbfb8aa3b, v35
	v_exp_f32_e32 v48, v46
	v_add_f32_e32 v45, 1.0, v45
	v_mul_f32_e32 v49, 0xbfb8aa3b, v36
	v_mul_f32_e32 v50, 0xbfb8aa3b, v41
	v_mul_f32_e32 v44, 0xbfb8aa3b, v38
	v_rcp_f32_e32 v46, v45
	v_add_f32_e32 v45, 1.0, v47
	v_add_f32_e32 v47, 1.0, v48
	v_mul_f32_e32 v48, 0xbfb8aa3b, v40
	v_exp_f32_e32 v49, v49
	v_exp_f32_e32 v51, v50
	v_mul_f32_e32 v50, 0xbfb8aa3b, v37
	v_exp_f32_e32 v44, v44
	v_exp_f32_e32 v48, v48
	v_exp_f32_e32 v52, v50
	v_add_f32_e32 v49, 1.0, v49
	v_add_f32_e32 v44, 1.0, v44
	v_add_f32_e32 v48, 1.0, v48
	v_rcp_f32_e32 v50, v49
	v_add_f32_e32 v49, 1.0, v51
	v_add_f32_e32 v51, 1.0, v52
	v_rcp_f32_e32 v44, v44
	v_rcp_f32_e32 v45, v45
	v_rcp_f32_e32 v47, v47
	v_rcp_f32_e32 v48, v48
	v_rcp_f32_e32 v49, v49
	v_rcp_f32_e32 v51, v51
	v_cvt_pk_bf16_f32 v34, v44, v45
	v_cvt_pk_bf16_f32 v35, v48, v49
	v_cvt_pk_bf16_f32 v36, v46, v47
	v_cvt_pk_bf16_f32 v37, v50, v51
; __device__ __forceinline__ unsigned cvt_pk_bf16(float lo, float hi) { const f32x2e_t v = {lo, hi}; return __builtin_bit_cast(unsigned, __builtin_convertvector(v, bf16x2e_t)); }
; __device__ __forceinline__ float fsigmoid(float v) { return __builtin_amdgcn_rcpf(1.f + __expf(-v)); }
; #define PG8_BAR __builtin_amdgcn_s_barrier()
;     __device__ __forceinline__ void operator()(const f32x4 (&acc)[2][2][4][2], const Unit& u, int wr, int wc, int fr, int fq) const {
;     ...
;             for (int m = 0; m < 4; ++m) { bf16_t* rowp = Z + (size_t)(row0 + ai * HALF + m * 16) * ldz + col0;
; #pragma unroll
;                 for (int bj = 0; bj < 2; ++bj) { f32x4 v0 = acc[ai][bj][m][0], v1 = acc[ai][bj][m][1];
;                     if (mode == 1) { v0 = v0 * 0.18033688011112042f; v1 = v1 * 0.18033688011112042f; }
;                     else if (mode == 2) {
; #pragma unroll
;                         for (int j = 0; j < 4; ++j) { v0[j] = v0[j] * fsigmoid(v0[j]); v1[j] = v1[j] * fsigmoid(v1[j]); } }
;                     else if (mode == 3) {
; #pragma unroll
;                         for (int j = 0; j < 4; ++j) { v0[j] = fsigmoid(v0[j]); v1[j] = fsigmoid(v1[j]); } }
;                     u32x4 w; w.x = cvt_pk_bf16(v0[0], v0[1]); w.y = cvt_pk_bf16(v0[2], v0[3]); w.z = cvt_pk_bf16(v1[0], v1[1]); w.w = cvt_pk_bf16(v1[2], v1[3]);
;                     *(u32x4*)(rowp + bj * HALF) = w; } }
; template <class Epi, class Sched, bool ALIGN_EPI = false, bool SP2 = false>
; __device__ __forceinline__ void gemm_phase(PG8_LAS unsigned char* lds, const Gemm g, const Sched& S, const Epi& E) {
;     ...
;         if constexpr (!Epi::AFTER_DRAIN) { E(acc, cur, wr, wc, fr, fq); S.done(cur); }
;         if (!has_next) break;
; #pragma unroll
;         for (int a = 0; a < 2; ++a)
; #pragma unroll
;             for (int b = 0; b < 2; ++b)
; #pragma unroll
;                 for (int m = 0; m < 4; ++m)
; #pragma unroll
;                     for (int n = 0; n < 2; ++n) acc[a][b][m][n] = (f32x4){0.f, 0.f, 0.f, 0.f};
;         cur = nxt; cA = nA; cB = nB; ++ui;
;         if constexpr (ALIGN_EPI) { if (wr == 1) PG8_BAR; }
	global_store_dwordx4 v[42:43], v[34:37], off offset:256
	v_mov_b32_e32 v41, v29
	v_mov_b32_e32 v40, v28
	v_mov_b32_e32 v37, v27
	v_mov_b32_e32 v36, v26
	v_mov_b32_e32 v39, v33
	v_mov_b32_e32 v38, v32
	v_mov_b32_e32 v35, v31
	v_mov_b32_e32 v34, v30
	v_mul_f32_e32 v35, 0xbfb8aa3b, v26
	v_mul_f32_e32 v36, 0xbfb8aa3b, v31
	v_exp_f32_e32 v35, v35
	v_exp_f32_e32 v37, v36
	v_mul_f32_e32 v36, 0xbfb8aa3b, v27
	v_exp_f32_e32 v38, v36
	v_add_f32_e32 v35, 1.0, v35
	v_mul_f32_e32 v39, 0xbfb8aa3b, v28
	v_mul_f32_e32 v40, 0xbfb8aa3b, v33
	v_mul_f32_e32 v34, 0xbfb8aa3b, v30
	v_rcp_f32_e32 v36, v35
	v_add_f32_e32 v35, 1.0, v37
	v_add_f32_e32 v37, 1.0, v38
	v_mul_f32_e32 v38, 0xbfb8aa3b, v32
	v_exp_f32_e32 v39, v39
	v_exp_f32_e32 v41, v40
	v_mul_f32_e32 v40, 0xbfb8aa3b, v29
	v_exp_f32_e32 v34, v34
	v_exp_f32_e32 v38, v38
	v_exp_f32_e32 v42, v40
	v_add_f32_e32 v39, 1.0, v39
	v_add_f32_e32 v34, 1.0, v34
	v_add_f32_e32 v38, 1.0, v38
	v_rcp_f32_e32 v40, v39
	v_add_f32_e32 v39, 1.0, v41
	v_add_f32_e32 v41, 1.0, v42
	v_rcp_f32_e32 v34, v34
	v_rcp_f32_e32 v35, v35
	v_rcp_f32_e32 v37, v37
	v_rcp_f32_e32 v38, v38
	v_rcp_f32_e32 v39, v39
	v_rcp_f32_e32 v41, v41
	v_add_u32_e32 v28, 0xa0, v168
	v_mov_b64_e32 v[26:27], s[92:93]
	v_mad_i64_i32 v[26:27], s[24:25], v28, s80, v[26:27]
	v_lshl_add_u64 v[26:27], v[122:123], 1, v[26:27]
	v_cvt_pk_bf16_f32 v28, v34, v35
	v_cvt_pk_bf16_f32 v29, v38, v39
	v_cvt_pk_bf16_f32 v30, v36, v37
	v_cvt_pk_bf16_f32 v31, v40, v41
	global_store_dwordx4 v[26:27], v[28:31], off
	v_mov_b32_e32 v35, v21
	v_mov_b32_e32 v34, v20
	v_mov_b32_e32 v31, v19
	v_mov_b32_e32 v30, v18
	v_mov_b32_e32 v33, v25
	v_mov_b32_e32 v32, v24
	v_mov_b32_e32 v29, v23
	v_mov_b32_e32 v28, v22
	v_mul_f32_e32 v29, 0xbfb8aa3b, v18
	v_mul_f32_e32 v30, 0xbfb8aa3b, v23
	v_exp_f32_e32 v29, v29
	v_exp_f32_e32 v31, v30
	v_mul_f32_e32 v30, 0xbfb8aa3b, v19
	v_exp_f32_e32 v32, v30
	v_add_f32_e32 v29, 1.0, v29
	v_mul_f32_e32 v33, 0xbfb8aa3b, v20
	v_mul_f32_e32 v34, 0xbfb8aa3b, v25
	v_mul_f32_e32 v28, 0xbfb8aa3b, v22
	v_rcp_f32_e32 v30, v29
	v_add_f32_e32 v29, 1.0, v31
	v_add_f32_e32 v31, 1.0, v32
	v_mul_f32_e32 v32, 0xbfb8aa3b, v24
	v_exp_f32_e32 v33, v33
	v_exp_f32_e32 v35, v34
	v_mul_f32_e32 v34, 0xbfb8aa3b, v21
	v_exp_f32_e32 v28, v28
	v_exp_f32_e32 v32, v32
	v_exp_f32_e32 v36, v34
	v_add_f32_e32 v33, 1.0, v33
	v_add_f32_e32 v28, 1.0, v28
	v_add_f32_e32 v32, 1.0, v32
	v_rcp_f32_e32 v34, v33
	v_add_f32_e32 v33, 1.0, v35
	v_add_f32_e32 v35, 1.0, v36
	v_rcp_f32_e32 v28, v28
	v_rcp_f32_e32 v29, v29
	v_rcp_f32_e32 v31, v31
	v_rcp_f32_e32 v32, v32
	v_rcp_f32_e32 v33, v33
	v_rcp_f32_e32 v35, v35
	v_cvt_pk_bf16_f32 v18, v28, v29
	v_cvt_pk_bf16_f32 v19, v32, v33
	v_cvt_pk_bf16_f32 v20, v30, v31
	v_cvt_pk_bf16_f32 v21, v34, v35
	global_store_dwordx4 v[26:27], v[18:21], off offset:256
	v_mov_b32_e32 v25, v13
	v_mov_b32_e32 v24, v12
	v_mov_b32_e32 v21, v11
	v_mov_b32_e32 v20, v10
	v_mov_b32_e32 v23, v17
	v_mov_b32_e32 v22, v16
	v_mov_b32_e32 v19, v15
	v_mov_b32_e32 v18, v14
	v_mul_f32_e32 v19, 0xbfb8aa3b, v10
	v_mul_f32_e32 v20, 0xbfb8aa3b, v15
	v_exp_f32_e32 v19, v19
	v_exp_f32_e32 v21, v20
	v_mul_f32_e32 v20, 0xbfb8aa3b, v11
	v_exp_f32_e32 v22, v20
	v_add_f32_e32 v19, 1.0, v19
	v_mul_f32_e32 v23, 0xbfb8aa3b, v12
	v_mul_f32_e32 v24, 0xbfb8aa3b, v17
	v_mul_f32_e32 v18, 0xbfb8aa3b, v14
	v_rcp_f32_e32 v20, v19
	v_add_f32_e32 v19, 1.0, v21
	v_add_f32_e32 v21, 1.0, v22
	v_mul_f32_e32 v22, 0xbfb8aa3b, v16
	v_exp_f32_e32 v23, v23
	v_exp_f32_e32 v25, v24
	v_mul_f32_e32 v24, 0xbfb8aa3b, v13
	v_exp_f32_e32 v18, v18
	v_exp_f32_e32 v22, v22
	v_exp_f32_e32 v26, v24
	v_add_f32_e32 v23, 1.0, v23
	v_add_f32_e32 v18, 1.0, v18
	v_add_f32_e32 v22, 1.0, v22
	v_rcp_f32_e32 v24, v23
	v_add_f32_e32 v23, 1.0, v25
	v_add_f32_e32 v25, 1.0, v26
	v_rcp_f32_e32 v18, v18
	v_rcp_f32_e32 v19, v19
	v_rcp_f32_e32 v21, v21
	v_rcp_f32_e32 v22, v22
	v_rcp_f32_e32 v23, v23
	v_rcp_f32_e32 v25, v25
	v_add_u32_e32 v12, 0xb0, v168
	v_mov_b64_e32 v[10:11], s[92:93]
	v_mad_i64_i32 v[10:11], s[24:25], v12, s80, v[10:11]
	v_lshl_add_u64 v[10:11], v[122:123], 1, v[10:11]
	v_cvt_pk_bf16_f32 v12, v18, v19
	v_cvt_pk_bf16_f32 v13, v22, v23
	v_cvt_pk_bf16_f32 v14, v20, v21
	v_cvt_pk_bf16_f32 v15, v24, v25
	global_store_dwordx4 v[10:11], v[12:15], off
	v_mov_b32_e32 v19, v5
	v_mov_b32_e32 v18, v4
	v_mov_b32_e32 v15, v3
	v_mov_b32_e32 v14, v2
	v_mov_b32_e32 v17, v9
	v_mov_b32_e32 v16, v8
	v_mov_b32_e32 v13, v7
	v_mov_b32_e32 v12, v6
	v_mul_f32_e32 v13, 0xbfb8aa3b, v2
	v_mul_f32_e32 v14, 0xbfb8aa3b, v7
	v_exp_f32_e32 v13, v13
	v_exp_f32_e32 v15, v14
	v_mul_f32_e32 v14, 0xbfb8aa3b, v3
	v_exp_f32_e32 v16, v14
	v_add_f32_e32 v13, 1.0, v13
	v_mul_f32_e32 v17, 0xbfb8aa3b, v4
	v_mul_f32_e32 v18, 0xbfb8aa3b, v9
	v_mul_f32_e32 v12, 0xbfb8aa3b, v6
	v_rcp_f32_e32 v14, v13
	v_add_f32_e32 v13, 1.0, v15
	v_add_f32_e32 v15, 1.0, v16
	v_mul_f32_e32 v16, 0xbfb8aa3b, v8
	v_exp_f32_e32 v17, v17
	v_exp_f32_e32 v19, v18
	v_mul_f32_e32 v18, 0xbfb8aa3b, v5
	v_exp_f32_e32 v12, v12
	v_exp_f32_e32 v16, v16
	v_exp_f32_e32 v20, v18
	v_add_f32_e32 v17, 1.0, v17
	v_add_f32_e32 v12, 1.0, v12
	v_add_f32_e32 v16, 1.0, v16
	v_rcp_f32_e32 v18, v17
	v_add_f32_e32 v17, 1.0, v19
	v_add_f32_e32 v19, 1.0, v20
	v_rcp_f32_e32 v12, v12
	v_rcp_f32_e32 v13, v13
	v_rcp_f32_e32 v15, v15
	v_rcp_f32_e32 v16, v16
	v_rcp_f32_e32 v17, v17
	v_rcp_f32_e32 v19, v19
	v_cvt_pk_bf16_f32 v2, v12, v13
	v_cvt_pk_bf16_f32 v3, v16, v17
	v_cvt_pk_bf16_f32 v4, v14, v15
	v_cvt_pk_bf16_f32 v5, v18, v19
	s_branch .Lepi_tail
.Lepi_tail:
	s_andn2_b64 vcc, exec, s[4:5]
	s_mov_b64 s[4:5], -1
	global_store_dwordx4 v[10:11], v[2:5], off offset:256
	s_cbranch_vccnz .LBB0_119
	s_andn2_b64 vcc, exec, s[0:1]
	s_cbranch_vccnz .LBB0_118
	s_barrier
	s_branch .LBB0_118
